# SwiGLU epilogues (P1,P9): 8 row-sumsq loads hoisted above align barrier, counted vmcnt(7) instead of vmcnt(0)
# speedup vs baseline: 1.0097x; 1.0097x over previous
.LBB0_227:
	s_add_u32 s54, s46, 0xfffc0080
	s_addc_u32 s55, s47, -1
	s_add_i32 s76, 16, 0x10000
	s_cmp_eq_u32 s78, 12
	s_cselect_b32 s61, s15, s55
	s_cselect_b32 s60, s72, s54
	v_add_u32_e32 v80, s76, v146
	s_cselect_b32 s55, s11, s75
	s_cselect_b32 s54, s73, s74
	s_add_i32 s77, 16, 0x14000
	ds_read_b128 v[142:145], v80
	ds_read_b128 v[148:151], v80 offset:1024
	ds_read_b128 v[160:163], v80 offset:2048
	ds_read_b128 v[164:167], v80 offset:3072
	v_add_u32_e32 v80, s77, v146
	ds_read_b128 v[168:171], v80
	ds_read_b128 v[172:175], v80 offset:1024
	ds_read_b128 v[176:179], v80 offset:2048
	ds_read_b128 v[180:183], v80 offset:3072
	v_lshl_add_u64 v[208:209], s[46:47], 0, v[138:139]
	s_add_i32 m0, s13, 0xc000
	ds_read_b128 v[184:187], v147
	ds_read_b128 v[188:191], v147 offset:1024
	ds_read_b128 v[204:207], v147 offset:2048
	ds_read_b128 v[214:217], v147 offset:3072
	ds_read_b128 v[218:221], v147 offset:4096
	ds_read_b128 v[222:225], v147 offset:5120
	ds_read_b128 v[226:229], v147 offset:6144
	ds_read_b128 v[230:233], v147 offset:7168
	global_load_lds_dwordx4 v[208:209], off
	v_lshl_add_u64 v[208:209], s[46:47], 0, v[140:141]
	s_add_i32 m0, s13, 0xe000
	s_nop 0
	global_load_lds_dwordx4 v[208:209], off
	s_waitcnt vmcnt(8)
	s_waitcnt lgkmcnt(0)
	s_barrier
	s_setprio 1
	s_waitcnt lgkmcnt(0)
	v_mfma_f32_16x16x32_bf16 v[118:121], v[142:145], v[184:187], v[118:121]
	v_mfma_f32_16x16x32_bf16 v[114:117], v[160:163], v[184:187], v[114:117]
	v_mfma_f32_16x16x32_bf16 v[106:109], v[142:145], v[204:207], v[106:109]
	v_mfma_f32_16x16x32_bf16 v[98:101], v[160:163], v[204:207], v[98:101]
	v_mfma_f32_16x16x32_bf16 v[90:93], v[142:145], v[218:221], v[90:93]
	v_mfma_f32_16x16x32_bf16 v[82:85], v[160:163], v[218:221], v[82:85]
	v_mfma_f32_16x16x32_bf16 v[68:71], v[142:145], v[226:229], v[68:71]
	v_mfma_f32_16x16x32_bf16 v[64:67], v[160:163], v[226:229], v[64:67]
	v_mfma_f32_16x16x32_bf16 v[118:121], v[148:151], v[188:191], v[118:121]
	v_mfma_f32_16x16x32_bf16 v[114:117], v[164:167], v[188:191], v[114:117]
	v_mfma_f32_16x16x32_bf16 v[106:109], v[148:151], v[214:217], v[106:109]
	v_mfma_f32_16x16x32_bf16 v[98:101], v[164:167], v[214:217], v[98:101]
	v_mfma_f32_16x16x32_bf16 v[90:93], v[148:151], v[222:225], v[90:93]
	v_mfma_f32_16x16x32_bf16 v[82:85], v[164:167], v[222:225], v[82:85]
	v_mfma_f32_16x16x32_bf16 v[68:71], v[148:151], v[230:233], v[68:71]
	v_mfma_f32_16x16x32_bf16 v[64:67], v[164:167], v[230:233], v[64:67]
	s_setprio 0
	s_setprio 1
	v_mfma_f32_16x16x32_bf16 v[126:129], v[168:171], v[184:187], v[126:129]
	v_mfma_f32_16x16x32_bf16 v[122:125], v[176:179], v[184:187], v[122:125]
	v_mfma_f32_16x16x32_bf16 v[110:113], v[168:171], v[204:207], v[110:113]
	v_mfma_f32_16x16x32_bf16 v[102:105], v[176:179], v[204:207], v[102:105]
	v_mfma_f32_16x16x32_bf16 v[94:97], v[168:171], v[218:221], v[94:97]
	v_mfma_f32_16x16x32_bf16 v[86:89], v[176:179], v[218:221], v[86:89]
	v_mfma_f32_16x16x32_bf16 v[76:79], v[168:171], v[226:229], v[76:79]
	v_mfma_f32_16x16x32_bf16 v[72:75], v[176:179], v[226:229], v[72:75]
	v_mfma_f32_16x16x32_bf16 v[126:129], v[172:175], v[188:191], v[126:129]
	v_mfma_f32_16x16x32_bf16 v[122:125], v[180:183], v[188:191], v[122:125]
	v_mfma_f32_16x16x32_bf16 v[110:113], v[172:175], v[214:217], v[110:113]
	v_mfma_f32_16x16x32_bf16 v[102:105], v[180:183], v[214:217], v[102:105]
	v_mfma_f32_16x16x32_bf16 v[94:97], v[172:175], v[222:225], v[94:97]
	v_mfma_f32_16x16x32_bf16 v[86:89], v[180:183], v[222:225], v[86:89]
	v_mfma_f32_16x16x32_bf16 v[76:79], v[172:175], v[230:233], v[76:79]
	v_mfma_f32_16x16x32_bf16 v[72:75], v[180:183], v[230:233], v[72:75]
	s_setprio 0
	s_barrier
	s_add_i32 s76, s76, s4
	v_lshl_add_u64 v[208:209], s[54:55], 0, v[134:135]
	s_mov_b32 m0, s76
	ds_read_b128 v[184:187], v147 offset:16384
	ds_read_b128 v[188:191], v147 offset:17408
	ds_read_b128 v[204:207], v147 offset:18432
	ds_read_b128 v[214:217], v147 offset:19456
	ds_read_b128 v[218:221], v147 offset:20480
	ds_read_b128 v[222:225], v147 offset:21504
	ds_read_b128 v[226:229], v147 offset:22528
	ds_read_b128 v[230:233], v147 offset:23552
	global_load_lds_dwordx4 v[208:209], off
	s_add_i32 m0, s76, 0x2000
	s_add_u32 s96, s54, 0x40000
	v_lshl_add_u64 v[234:235], s[54:55], 0, v[130:131]
	s_addc_u32 s97, s55, 0
	s_add_i32 s76, s77, s4
	global_load_lds_dwordx4 v[234:235], off
	v_lshl_add_u64 v[236:237], s[96:97], 0, v[134:135]
	s_mov_b32 m0, s76
	v_lshl_add_u64 v[238:239], s[60:61], 0, v[132:133]
	global_load_lds_dwordx4 v[236:237], off
	v_lshl_add_u64 v[236:237], s[96:97], 0, v[130:131]
	s_add_i32 m0, s76, 0x2000
	s_nop 0
	global_load_lds_dwordx4 v[236:237], off
	v_lshl_add_u64 v[236:237], s[60:61], 0, v[136:137]
	s_mov_b32 m0, s13
	s_nop 0
	global_load_lds_dwordx4 v[236:237], off
	s_mov_b32 m0, s25
	s_nop 0
	global_load_lds_dwordx4 v[238:239], off
	s_waitcnt vmcnt(8)
	s_waitcnt lgkmcnt(0)
	s_barrier
	s_setprio 1
	s_waitcnt lgkmcnt(0)
	v_mfma_f32_16x16x32_bf16 v[52:55], v[142:145], v[184:187], v[52:55]
	v_mfma_f32_16x16x32_bf16 v[48:51], v[160:163], v[184:187], v[48:51]
	v_mfma_f32_16x16x32_bf16 v[36:39], v[142:145], v[204:207], v[36:39]
	v_mfma_f32_16x16x32_bf16 v[32:35], v[160:163], v[204:207], v[32:35]
	v_mfma_f32_16x16x32_bf16 v[20:23], v[142:145], v[218:221], v[20:23]
	v_mfma_f32_16x16x32_bf16 v[16:19], v[160:163], v[218:221], v[16:19]
	v_mfma_f32_16x16x32_bf16 v[8:11], v[142:145], v[226:229], v[8:11]
	v_mfma_f32_16x16x32_bf16 v[0:3], v[160:163], v[226:229], v[0:3]
	v_mfma_f32_16x16x32_bf16 v[52:55], v[148:151], v[188:191], v[52:55]
	v_mfma_f32_16x16x32_bf16 v[48:51], v[164:167], v[188:191], v[48:51]
	v_mfma_f32_16x16x32_bf16 v[36:39], v[148:151], v[214:217], v[36:39]
	v_mfma_f32_16x16x32_bf16 v[32:35], v[164:167], v[214:217], v[32:35]
	v_mfma_f32_16x16x32_bf16 v[20:23], v[148:151], v[222:225], v[20:23]
	v_mfma_f32_16x16x32_bf16 v[16:19], v[164:167], v[222:225], v[16:19]
	v_mfma_f32_16x16x32_bf16 v[8:11], v[148:151], v[230:233], v[8:11]
	v_mfma_f32_16x16x32_bf16 v[0:3], v[164:167], v[230:233], v[0:3]
	s_setprio 0
	s_setprio 1
	v_mfma_f32_16x16x32_bf16 v[60:63], v[168:171], v[184:187], v[60:63]
	v_mfma_f32_16x16x32_bf16 v[56:59], v[176:179], v[184:187], v[56:59]
	v_mfma_f32_16x16x32_bf16 v[44:47], v[168:171], v[204:207], v[44:47]
	v_mfma_f32_16x16x32_bf16 v[40:43], v[176:179], v[204:207], v[40:43]
	v_mfma_f32_16x16x32_bf16 v[28:31], v[168:171], v[218:221], v[28:31]
	v_mfma_f32_16x16x32_bf16 v[24:27], v[176:179], v[218:221], v[24:27]
	v_mfma_f32_16x16x32_bf16 v[12:15], v[168:171], v[226:229], v[12:15]
	v_mfma_f32_16x16x32_bf16 v[4:7], v[176:179], v[226:229], v[4:7]
	v_mfma_f32_16x16x32_bf16 v[60:63], v[172:175], v[188:191], v[60:63]
	v_mfma_f32_16x16x32_bf16 v[56:59], v[180:183], v[188:191], v[56:59]
	v_mfma_f32_16x16x32_bf16 v[44:47], v[172:175], v[214:217], v[44:47]
	v_mfma_f32_16x16x32_bf16 v[40:43], v[180:183], v[214:217], v[40:43]
	v_mfma_f32_16x16x32_bf16 v[28:31], v[172:175], v[222:225], v[28:31]
	v_mfma_f32_16x16x32_bf16 v[24:27], v[180:183], v[222:225], v[24:27]
	v_mfma_f32_16x16x32_bf16 v[12:15], v[172:175], v[230:233], v[12:15]
	v_mfma_f32_16x16x32_bf16 v[4:7], v[180:183], v[230:233], v[4:7]
	s_setprio 0
	s_barrier
	s_add_i32 s76, 16, 0x18000
	v_add_u32_e32 v80, s76, v146
	s_add_i32 s77, 16, 0x1c000
	ds_read_b128 v[142:145], v80
	ds_read_b128 v[148:151], v80 offset:1024
	ds_read_b128 v[160:163], v80 offset:2048
	ds_read_b128 v[164:167], v80 offset:3072
	v_add_u32_e32 v80, s77, v146
	ds_read_b128 v[168:171], v80
	ds_read_b128 v[172:175], v80 offset:1024
	ds_read_b128 v[176:179], v80 offset:2048
	ds_read_b128 v[180:183], v80 offset:3072
	s_add_u32 s60, s60, 0x40000
	s_addc_u32 s61, s61, 0
	s_mov_b32 m0, s30
	v_lshl_add_u64 v[240:241], s[60:61], 0, v[136:137]
	ds_read_b128 v[184:187], v147 offset:32768
	ds_read_b128 v[188:191], v147 offset:33792
	ds_read_b128 v[204:207], v147 offset:34816
	ds_read_b128 v[214:217], v147 offset:35840
	ds_read_b128 v[218:221], v147 offset:36864
	ds_read_b128 v[222:225], v147 offset:37888
	ds_read_b128 v[226:229], v147 offset:38912
	ds_read_b128 v[230:233], v147 offset:39936
	global_load_lds_dwordx4 v[240:241], off
	v_lshl_add_u64 v[240:241], s[60:61], 0, v[132:133]
	s_mov_b32 m0, s33
	s_nop 0
	global_load_lds_dwordx4 v[240:241], off
	s_waitcnt vmcnt(8)
	s_waitcnt lgkmcnt(0)
	s_barrier
	s_setprio 1
	s_waitcnt lgkmcnt(0)
	v_mfma_f32_16x16x32_bf16 v[118:121], v[142:145], v[184:187], v[118:121]
	v_mfma_f32_16x16x32_bf16 v[114:117], v[160:163], v[184:187], v[114:117]
	v_mfma_f32_16x16x32_bf16 v[106:109], v[142:145], v[204:207], v[106:109]
	v_mfma_f32_16x16x32_bf16 v[98:101], v[160:163], v[204:207], v[98:101]
	v_mfma_f32_16x16x32_bf16 v[90:93], v[142:145], v[218:221], v[90:93]
	v_mfma_f32_16x16x32_bf16 v[82:85], v[160:163], v[218:221], v[82:85]
	v_mfma_f32_16x16x32_bf16 v[68:71], v[142:145], v[226:229], v[68:71]
	v_mfma_f32_16x16x32_bf16 v[64:67], v[160:163], v[226:229], v[64:67]
	v_mfma_f32_16x16x32_bf16 v[118:121], v[148:151], v[188:191], v[118:121]
	v_mfma_f32_16x16x32_bf16 v[114:117], v[164:167], v[188:191], v[114:117]
	v_mfma_f32_16x16x32_bf16 v[106:109], v[148:151], v[214:217], v[106:109]
	v_mfma_f32_16x16x32_bf16 v[98:101], v[164:167], v[214:217], v[98:101]
	v_mfma_f32_16x16x32_bf16 v[90:93], v[148:151], v[222:225], v[90:93]
	v_mfma_f32_16x16x32_bf16 v[82:85], v[164:167], v[222:225], v[82:85]
	v_mfma_f32_16x16x32_bf16 v[68:71], v[148:151], v[230:233], v[68:71]
	v_mfma_f32_16x16x32_bf16 v[64:67], v[164:167], v[230:233], v[64:67]
	s_setprio 0
	s_setprio 1
	v_mfma_f32_16x16x32_bf16 v[126:129], v[168:171], v[184:187], v[126:129]
	v_mfma_f32_16x16x32_bf16 v[122:125], v[176:179], v[184:187], v[122:125]
	v_mfma_f32_16x16x32_bf16 v[110:113], v[168:171], v[204:207], v[110:113]
	v_mfma_f32_16x16x32_bf16 v[102:105], v[176:179], v[204:207], v[102:105]
	v_mfma_f32_16x16x32_bf16 v[94:97], v[168:171], v[218:221], v[94:97]
	v_mfma_f32_16x16x32_bf16 v[86:89], v[176:179], v[218:221], v[86:89]
	v_mfma_f32_16x16x32_bf16 v[76:79], v[168:171], v[226:229], v[76:79]
	v_mfma_f32_16x16x32_bf16 v[72:75], v[176:179], v[226:229], v[72:75]
	v_mfma_f32_16x16x32_bf16 v[126:129], v[172:175], v[188:191], v[126:129]
	v_mfma_f32_16x16x32_bf16 v[122:125], v[180:183], v[188:191], v[122:125]
	v_mfma_f32_16x16x32_bf16 v[110:113], v[172:175], v[214:217], v[110:113]
	v_mfma_f32_16x16x32_bf16 v[102:105], v[180:183], v[214:217], v[102:105]
	v_mfma_f32_16x16x32_bf16 v[94:97], v[172:175], v[222:225], v[94:97]
	v_mfma_f32_16x16x32_bf16 v[86:89], v[180:183], v[222:225], v[86:89]
	v_mfma_f32_16x16x32_bf16 v[76:79], v[172:175], v[230:233], v[76:79]
	v_mfma_f32_16x16x32_bf16 v[72:75], v[180:183], v[230:233], v[72:75]
	s_setprio 0
	s_barrier
	s_add_i32 s60, s76, s4
	v_lshl_add_u64 v[208:209], v[208:209], 0, s[20:21]
	s_mov_b32 m0, s60
	ds_read_b128 v[184:187], v147 offset:49152
	ds_read_b128 v[188:191], v147 offset:50176
	ds_read_b128 v[204:207], v147 offset:51200
	ds_read_b128 v[214:217], v147 offset:52224
	ds_read_b128 v[218:221], v147 offset:53248
	ds_read_b128 v[222:225], v147 offset:54272
	ds_read_b128 v[226:229], v147 offset:55296
	ds_read_b128 v[230:233], v147 offset:56320
	global_load_lds_dwordx4 v[208:209], off
	s_add_i32 m0, s60, 0x2000
	s_add_u32 s54, s54, 0x40080
	v_lshl_add_u64 v[208:209], v[234:235], 0, s[20:21]
	s_addc_u32 s55, s55, 0
	s_add_i32 s60, s77, s4
	global_load_lds_dwordx4 v[208:209], off
	v_lshl_add_u64 v[208:209], s[54:55], 0, v[134:135]
	s_mov_b32 m0, s60
	s_nop 0
	global_load_lds_dwordx4 v[208:209], off
	v_lshl_add_u64 v[208:209], s[54:55], 0, v[130:131]
	s_add_i32 m0, s60, 0x2000
	s_nop 0
	global_load_lds_dwordx4 v[208:209], off
	v_lshl_add_u64 v[208:209], v[236:237], 0, s[20:21]
	s_mov_b32 m0, s34
	s_nop 0
	global_load_lds_dwordx4 v[208:209], off
	v_lshl_add_u64 v[208:209], v[238:239], 0, s[20:21]
	s_mov_b32 m0, s36
	s_nop 0
	global_load_lds_dwordx4 v[208:209], off
	s_waitcnt vmcnt(8)
	s_waitcnt lgkmcnt(0)
	s_barrier
	s_setprio 1
	s_waitcnt lgkmcnt(0)
	v_mfma_f32_16x16x32_bf16 v[52:55], v[142:145], v[184:187], v[52:55]
	v_mfma_f32_16x16x32_bf16 v[48:51], v[160:163], v[184:187], v[48:51]
	v_mfma_f32_16x16x32_bf16 v[36:39], v[142:145], v[204:207], v[36:39]
	v_mfma_f32_16x16x32_bf16 v[32:35], v[160:163], v[204:207], v[32:35]
	v_mfma_f32_16x16x32_bf16 v[20:23], v[142:145], v[218:221], v[20:23]
	v_mfma_f32_16x16x32_bf16 v[16:19], v[160:163], v[218:221], v[16:19]
	v_mfma_f32_16x16x32_bf16 v[8:11], v[142:145], v[226:229], v[8:11]
	v_mfma_f32_16x16x32_bf16 v[0:3], v[160:163], v[226:229], v[0:3]
	v_mfma_f32_16x16x32_bf16 v[52:55], v[148:151], v[188:191], v[52:55]
	v_mfma_f32_16x16x32_bf16 v[48:51], v[164:167], v[188:191], v[48:51]
	v_mfma_f32_16x16x32_bf16 v[36:39], v[148:151], v[214:217], v[36:39]
	v_mfma_f32_16x16x32_bf16 v[32:35], v[164:167], v[214:217], v[32:35]
	v_mfma_f32_16x16x32_bf16 v[20:23], v[148:151], v[222:225], v[20:23]
	v_mfma_f32_16x16x32_bf16 v[16:19], v[164:167], v[222:225], v[16:19]
	v_mfma_f32_16x16x32_bf16 v[8:11], v[148:151], v[230:233], v[8:11]
	v_mfma_f32_16x16x32_bf16 v[0:3], v[164:167], v[230:233], v[0:3]
	s_setprio 0
	s_setprio 1
	v_mfma_f32_16x16x32_bf16 v[60:63], v[168:171], v[184:187], v[60:63]
	v_mfma_f32_16x16x32_bf16 v[56:59], v[176:179], v[184:187], v[56:59]
	v_mfma_f32_16x16x32_bf16 v[44:47], v[168:171], v[204:207], v[44:47]
	v_mfma_f32_16x16x32_bf16 v[40:43], v[176:179], v[204:207], v[40:43]
	v_mfma_f32_16x16x32_bf16 v[28:31], v[168:171], v[218:221], v[28:31]
	v_mfma_f32_16x16x32_bf16 v[24:27], v[176:179], v[218:221], v[24:27]
	v_mfma_f32_16x16x32_bf16 v[12:15], v[168:171], v[226:229], v[12:15]
	v_mfma_f32_16x16x32_bf16 v[4:7], v[176:179], v[226:229], v[4:7]
	v_mfma_f32_16x16x32_bf16 v[60:63], v[172:175], v[188:191], v[60:63]
	v_mfma_f32_16x16x32_bf16 v[56:59], v[180:183], v[188:191], v[56:59]
	v_mfma_f32_16x16x32_bf16 v[44:47], v[172:175], v[214:217], v[44:47]
	v_mfma_f32_16x16x32_bf16 v[40:43], v[180:183], v[214:217], v[40:43]
	v_mfma_f32_16x16x32_bf16 v[28:31], v[172:175], v[222:225], v[28:31]
	v_mfma_f32_16x16x32_bf16 v[24:27], v[180:183], v[222:225], v[24:27]
	v_mfma_f32_16x16x32_bf16 v[12:15], v[172:175], v[230:233], v[12:15]
	v_mfma_f32_16x16x32_bf16 v[4:7], v[180:183], v[230:233], v[4:7]
	s_setprio 0
	s_barrier
	s_add_i32 s78, s78, 2
	s_add_u32 s46, s46, 0x100
	s_addc_u32 s47, s47, 0
	s_add_u32 s74, s74, 0x100
	s_addc_u32 s75, s75, 0
	s_cmp_gt_u32 s78, 13
	s_cbranch_scc0 .LBB0_227
	v_mov_b32_e32 v160, v192
	s_lshl_b32 s11, s67, 8
	v_mov_b32_e32 v151, v116
	v_ashrrev_i32_e32 v80, 2, v160
	v_and_b32_e32 v80, 0xffffffc0, v80
	v_and_or_b32 v142, v160, 15, s11
	v_add_u32_e32 v142, v142, v80
	v_ashrrev_i32_e32 v143, 31, v142
	v_lshl_add_u64 v[144:145], v[142:143], 2, s[90:91]
	v_add_co_u32_e32 v144, vcc, 0x40000, v144
	v_mov_b32_e32 v116, v125
	s_nop 0
	v_addc_co_u32_e32 v145, vcc, 0, v145, vcc
	global_load_dword v242, v[144:145], off
	global_load_dword v243, v[144:145], off offset:64
	global_load_dword v244, v[144:145], off offset:128
	global_load_dword v245, v[144:145], off offset:192
	global_load_dword v246, v[144:145], off offset:512
	global_load_dword v247, v[144:145], off offset:576
	global_load_dword v248, v[144:145], off offset:640
	global_load_dword v249, v[144:145], off offset:704
	s_and_b64 vcc, exec, s[6:7]
	s_cbranch_vccz .LBB0_230
	s_barrier
.LBB0_230:
	v_mov_b32_e32 v148, v126
	v_mov_b32_e32 v149, v118
	v_mov_b32_e32 v118, v127
	v_mov_b32_e32 v126, v128
	v_mov_b32_e32 v127, v120
	v_mov_b32_e32 v120, v129
	v_mov_b32_e32 v128, v122
	v_mov_b32_e32 v129, v114
	v_mov_b32_e32 v114, v123
	v_mov_b32_e32 v150, v124
	v_readlane_b32 s54, v254, 40
	s_lshl_b32 s46, s66, 7
	v_readlane_b32 s55, v254, 41
	s_ashr_i32 s47, s46, 31
	s_lshl_b64 s[46:47], s[46:47], 1
	v_mov_b64_e32 v[122:123], s[54:55]
	v_and_b32_e32 v80, 0xc0, v160
	v_and_b32_e32 v124, 48, v160
	v_mad_i64_i32 v[160:161], s[54:55], v142, s28, v[122:123]
	v_lshl_add_u64 v[160:161], v[160:161], 0, s[46:47]
	v_mov_b32_e32 v125, v81
	v_lshl_add_u64 v[160:161], v[160:161], 0, v[80:81]
	v_lshl_add_u64 v[160:161], v[160:161], 0, v[124:125]
	s_waitcnt vmcnt(7)
	v_fmamk_f32 v143, v242, 0x3a800000, v194
	v_mul_f32_e32 v162, 0x4b800000, v143
	v_cmp_gt_f32_e32 vcc, s19, v143
	s_nop 1
	v_cndmask_b32_e32 v143, v143, v162, vcc
	v_rsq_f32_e32 v143, v143
	s_nop 0
	v_mul_f32_e32 v162, 0x45800000, v143
	v_cndmask_b32_e32 v162, v143, v162, vcc
	v_pk_mul_f32 v[116:117], v[116:117], v[162:163] op_sel_hi:[1,0]
	v_pk_mul_f32 v[148:149], v[148:149], v[162:163] op_sel_hi:[1,0]
	v_pk_mul_f32 v[118:119], v[118:119], v[162:163] op_sel_hi:[1,0]
	v_pk_mul_f32 v[126:127], v[126:127], v[162:163] op_sel_hi:[1,0]
	v_pk_mul_f32 v[120:121], v[120:121], v[162:163] op_sel_hi:[1,0]
	v_pk_mul_f32 v[128:129], v[128:129], v[162:163] op_sel_hi:[1,0]
	v_pk_mul_f32 v[114:115], v[114:115], v[162:163] op_sel_hi:[1,0]
	v_pk_mul_f32 v[150:151], v[150:151], v[162:163] op_sel_hi:[1,0]
	v_mul_f32_e32 v168, 0xbfb8aa3b, v117
	v_mul_f32_e32 v143, 0xbfb8aa3b, v149
	v_mul_f32_e32 v162, 0xbfb8aa3b, v119
	v_mul_f32_e32 v163, 0xbfb8aa3b, v127
	v_mul_f32_e32 v164, 0xbfb8aa3b, v121
	v_mul_f32_e32 v165, 0xbfb8aa3b, v129
	v_mul_f32_e32 v166, 0xbfb8aa3b, v115
	v_mul_f32_e32 v167, 0xbfb8aa3b, v151
	v_exp_f32_e32 v168, v168
	v_exp_f32_e32 v143, v143
	v_exp_f32_e32 v162, v162
	v_exp_f32_e32 v163, v163
	v_exp_f32_e32 v164, v164
	v_exp_f32_e32 v165, v165
	v_exp_f32_e32 v166, v166
	v_exp_f32_e32 v167, v167
	v_add_f32_e32 v168, 1.0, v168
	v_add_f32_e32 v143, 1.0, v143
	v_add_f32_e32 v162, 1.0, v162
	v_add_f32_e32 v163, 1.0, v163
	v_add_f32_e32 v164, 1.0, v164
	v_add_f32_e32 v165, 1.0, v165
	v_add_f32_e32 v166, 1.0, v166
	v_add_f32_e32 v167, 1.0, v167
	v_rcp_f32_e32 v168, v168
	v_rcp_f32_e32 v143, v143
	v_rcp_f32_e32 v162, v162
	v_rcp_f32_e32 v163, v163
	v_rcp_f32_e32 v164, v164
	v_rcp_f32_e32 v165, v165
	v_rcp_f32_e32 v166, v166
	v_rcp_f32_e32 v167, v167
	v_mul_f32_e32 v117, v117, v168
	v_mul_f32_e32 v143, v149, v143
	v_mul_f32_e32 v119, v119, v162
	v_mul_f32_e32 v127, v127, v163
	v_mul_f32_e32 v121, v121, v164
	v_mul_f32_e32 v129, v129, v165
	v_mul_f32_e32 v115, v115, v166
	v_mul_f32_e32 v149, v151, v167
	v_mul_f32_e32 v117, v116, v117
	v_mul_f32_e32 v143, v148, v143
	v_mul_f32_e32 v118, v118, v119
	v_mul_f32_e32 v119, v126, v127
	v_mul_f32_e32 v120, v120, v121
	v_mul_f32_e32 v121, v128, v129
	v_mul_f32_e32 v126, v114, v115
	v_mul_f32_e32 v127, v150, v149
	v_cvt_pk_bf16_f32 v114, v143, v118
	v_cvt_pk_bf16_f32 v115, v119, v120
	v_cvt_pk_bf16_f32 v116, v121, v126
	v_cvt_pk_bf16_f32 v117, v127, v117
	global_store_dwordx4 v[160:161], v[114:117], off nt
	s_nop 0
	s_nop 0
	v_mov_b32_e32 v115, v106
	v_mov_b32_e32 v106, v111
	v_mov_b32_e32 v111, v108
	v_mov_b32_e32 v108, v113
	v_mov_b32_e32 v113, v98
	v_mov_b32_e32 v98, v103
	v_mov_b32_e32 v103, v100
	v_mov_b32_e32 v100, v105
	v_mov_b32_e32 v114, v110
	v_mov_b32_e32 v110, v112
	v_mov_b32_e32 v112, v102
	v_mov_b32_e32 v102, v104
	v_or_b32_e32 v104, 16, v142
	v_mad_i64_i32 v[104:105], s[54:55], v104, s28, v[122:123]
	v_lshl_add_u64 v[104:105], v[104:105], 0, s[46:47]
	v_lshl_add_u64 v[104:105], v[104:105], 0, v[80:81]
	v_lshl_add_u64 v[104:105], v[104:105], 0, v[124:125]
	s_waitcnt vmcnt(7)
	v_fmamk_f32 v116, v243, 0x3a800000, v194
	v_mul_f32_e32 v117, 0x4b800000, v116
	v_cmp_gt_f32_e32 vcc, s19, v116
	s_nop 1
	v_cndmask_b32_e32 v116, v116, v117, vcc
	v_rsq_f32_e32 v116, v116
	s_nop 0
	v_mul_f32_e32 v117, 0x45800000, v116
	v_cndmask_b32_e32 v116, v116, v117, vcc
	v_pk_mul_f32 v[100:101], v[100:101], v[116:117] op_sel_hi:[1,0]
	v_pk_mul_f32 v[114:115], v[114:115], v[116:117] op_sel_hi:[1,0]
	v_pk_mul_f32 v[106:107], v[106:107], v[116:117] op_sel_hi:[1,0]
	v_pk_mul_f32 v[110:111], v[110:111], v[116:117] op_sel_hi:[1,0]
	v_pk_mul_f32 v[108:109], v[108:109], v[116:117] op_sel_hi:[1,0]
	v_pk_mul_f32 v[112:113], v[112:113], v[116:117] op_sel_hi:[1,0]
	v_pk_mul_f32 v[98:99], v[98:99], v[116:117] op_sel_hi:[1,0]
	v_pk_mul_f32 v[102:103], v[102:103], v[116:117] op_sel_hi:[1,0]
	v_mul_f32_e32 v127, 0xbfb8aa3b, v101
	v_mul_f32_e32 v116, 0xbfb8aa3b, v115
	v_mul_f32_e32 v117, 0xbfb8aa3b, v107
	v_mul_f32_e32 v118, 0xbfb8aa3b, v111
	v_mul_f32_e32 v119, 0xbfb8aa3b, v109
	v_mul_f32_e32 v120, 0xbfb8aa3b, v113
	v_mul_f32_e32 v121, 0xbfb8aa3b, v99
	v_mul_f32_e32 v126, 0xbfb8aa3b, v103
	v_exp_f32_e32 v127, v127
	v_exp_f32_e32 v116, v116
	v_exp_f32_e32 v117, v117
	v_exp_f32_e32 v118, v118
	v_exp_f32_e32 v119, v119
	v_exp_f32_e32 v120, v120
	v_exp_f32_e32 v121, v121
	v_exp_f32_e32 v126, v126
	v_add_f32_e32 v127, 1.0, v127
	v_add_f32_e32 v116, 1.0, v116
	v_add_f32_e32 v117, 1.0, v117
	v_add_f32_e32 v118, 1.0, v118
	v_add_f32_e32 v119, 1.0, v119
	v_add_f32_e32 v120, 1.0, v120
	v_add_f32_e32 v121, 1.0, v121
	v_add_f32_e32 v126, 1.0, v126
	v_rcp_f32_e32 v127, v127
	v_rcp_f32_e32 v116, v116
	v_rcp_f32_e32 v117, v117
	v_rcp_f32_e32 v118, v118
	v_rcp_f32_e32 v119, v119
	v_rcp_f32_e32 v120, v120
	v_rcp_f32_e32 v121, v121
	v_rcp_f32_e32 v126, v126
	v_mul_f32_e32 v101, v101, v127
	v_mul_f32_e32 v115, v115, v116
	v_mul_f32_e32 v107, v107, v117
	v_mul_f32_e32 v111, v111, v118
	v_mul_f32_e32 v109, v109, v119
	v_mul_f32_e32 v113, v113, v120
	v_mul_f32_e32 v99, v99, v121
	v_mul_f32_e32 v103, v103, v126
	v_mul_f32_e32 v101, v100, v101
	v_mul_f32_e32 v114, v114, v115
	v_mul_f32_e32 v106, v106, v107
	v_mul_f32_e32 v107, v110, v111
	v_mul_f32_e32 v108, v108, v109
	v_mul_f32_e32 v109, v112, v113
	v_mul_f32_e32 v110, v98, v99
	v_mul_f32_e32 v102, v102, v103
	v_cvt_pk_bf16_f32 v98, v114, v106
	v_cvt_pk_bf16_f32 v99, v107, v108
	v_cvt_pk_bf16_f32 v100, v109, v110
	v_cvt_pk_bf16_f32 v101, v102, v101
	global_store_dwordx4 v[104:105], v[98:101], off nt
	s_nop 0
	s_nop 0
	v_mov_b32_e32 v99, v90
	v_mov_b32_e32 v90, v95
	v_mov_b32_e32 v95, v92
	v_mov_b32_e32 v92, v97
	v_mov_b32_e32 v97, v82
	v_mov_b32_e32 v82, v87
	v_mov_b32_e32 v87, v84
	v_mov_b32_e32 v84, v89
	v_mov_b32_e32 v98, v94
	v_mov_b32_e32 v94, v96
	v_mov_b32_e32 v96, v86
	v_mov_b32_e32 v86, v88
	v_or_b32_e32 v88, 32, v142
	v_mad_i64_i32 v[88:89], s[54:55], v88, s28, v[122:123]
	v_lshl_add_u64 v[88:89], v[88:89], 0, s[46:47]
	v_lshl_add_u64 v[88:89], v[88:89], 0, v[80:81]
	v_lshl_add_u64 v[88:89], v[88:89], 0, v[124:125]
	s_waitcnt vmcnt(7)
	v_fmamk_f32 v100, v244, 0x3a800000, v194
	v_mul_f32_e32 v101, 0x4b800000, v100
	v_cmp_gt_f32_e32 vcc, s19, v100
	s_nop 1
	v_cndmask_b32_e32 v100, v100, v101, vcc
	v_rsq_f32_e32 v100, v100
	s_nop 0
	v_mul_f32_e32 v101, 0x45800000, v100
	v_cndmask_b32_e32 v100, v100, v101, vcc
	v_pk_mul_f32 v[84:85], v[84:85], v[100:101] op_sel_hi:[1,0]
	v_pk_mul_f32 v[98:99], v[98:99], v[100:101] op_sel_hi:[1,0]
	v_pk_mul_f32 v[90:91], v[90:91], v[100:101] op_sel_hi:[1,0]
	v_pk_mul_f32 v[94:95], v[94:95], v[100:101] op_sel_hi:[1,0]
	v_pk_mul_f32 v[92:93], v[92:93], v[100:101] op_sel_hi:[1,0]
	v_pk_mul_f32 v[96:97], v[96:97], v[100:101] op_sel_hi:[1,0]
	v_pk_mul_f32 v[82:83], v[82:83], v[100:101] op_sel_hi:[1,0]
	v_pk_mul_f32 v[86:87], v[86:87], v[100:101] op_sel_hi:[1,0]
	v_mul_f32_e32 v107, 0xbfb8aa3b, v85
	v_mul_f32_e32 v100, 0xbfb8aa3b, v99
	v_mul_f32_e32 v101, 0xbfb8aa3b, v91
	v_mul_f32_e32 v102, 0xbfb8aa3b, v95
	v_mul_f32_e32 v103, 0xbfb8aa3b, v93
	v_mul_f32_e32 v104, 0xbfb8aa3b, v97
	v_mul_f32_e32 v105, 0xbfb8aa3b, v83
	v_mul_f32_e32 v106, 0xbfb8aa3b, v87
	v_exp_f32_e32 v107, v107
	v_exp_f32_e32 v100, v100
	v_exp_f32_e32 v101, v101
	v_exp_f32_e32 v102, v102
	v_exp_f32_e32 v103, v103
	v_exp_f32_e32 v104, v104
	v_exp_f32_e32 v105, v105
	v_exp_f32_e32 v106, v106
	v_add_f32_e32 v107, 1.0, v107
	v_add_f32_e32 v100, 1.0, v100
	v_add_f32_e32 v101, 1.0, v101
	v_add_f32_e32 v102, 1.0, v102
	v_add_f32_e32 v103, 1.0, v103
	v_add_f32_e32 v104, 1.0, v104
	v_add_f32_e32 v105, 1.0, v105
	v_add_f32_e32 v106, 1.0, v106
	v_rcp_f32_e32 v107, v107
	v_rcp_f32_e32 v100, v100
	v_rcp_f32_e32 v101, v101
	v_rcp_f32_e32 v102, v102
	v_rcp_f32_e32 v103, v103
	v_rcp_f32_e32 v104, v104
	v_rcp_f32_e32 v105, v105
	v_rcp_f32_e32 v106, v106
	v_mul_f32_e32 v85, v85, v107
	v_mul_f32_e32 v99, v99, v100
	v_mul_f32_e32 v91, v91, v101
	v_mul_f32_e32 v95, v95, v102
	v_mul_f32_e32 v93, v93, v103
	v_mul_f32_e32 v97, v97, v104
	v_mul_f32_e32 v83, v83, v105
	v_mul_f32_e32 v87, v87, v106
	v_mul_f32_e32 v85, v84, v85
	v_mul_f32_e32 v98, v98, v99
	v_mul_f32_e32 v90, v90, v91
	v_mul_f32_e32 v91, v94, v95
	v_mul_f32_e32 v92, v92, v93
	v_mul_f32_e32 v93, v96, v97
	v_mul_f32_e32 v94, v82, v83
	v_mul_f32_e32 v86, v86, v87
	v_cvt_pk_bf16_f32 v82, v98, v90
	v_cvt_pk_bf16_f32 v83, v91, v92
	v_cvt_pk_bf16_f32 v84, v93, v94
	v_cvt_pk_bf16_f32 v85, v86, v85
	global_store_dwordx4 v[88:89], v[82:85], off nt
	s_nop 0
	s_waitcnt vmcnt(7)
	v_fmamk_f32 v86, v245, 0x3a800000, v194
	v_mul_f32_e32 v87, 0x4b800000, v86
	v_cmp_gt_f32_e32 vcc, s19, v86
	v_mov_b32_e32 v83, v68
	v_mov_b32_e32 v68, v77
	v_cndmask_b32_e32 v86, v86, v87, vcc
	v_rsq_f32_e32 v86, v86
	v_mov_b32_e32 v77, v70
	v_mov_b32_e32 v70, v79
	v_mov_b32_e32 v79, v64
	v_mul_f32_e32 v87, 0x45800000, v86
	v_mov_b32_e32 v64, v73
	v_mov_b32_e32 v73, v66
	v_mov_b32_e32 v66, v75
	v_cndmask_b32_e32 v86, v86, v87, vcc
	v_mov_b32_e32 v82, v76
	v_mov_b32_e32 v76, v78
	v_mov_b32_e32 v78, v72
	v_mov_b32_e32 v72, v74
	v_pk_mul_f32 v[66:67], v[66:67], v[86:87] op_sel_hi:[1,0]
	v_pk_mul_f32 v[82:83], v[82:83], v[86:87] op_sel_hi:[1,0]
	v_pk_mul_f32 v[68:69], v[68:69], v[86:87] op_sel_hi:[1,0]
	v_pk_mul_f32 v[76:77], v[76:77], v[86:87] op_sel_hi:[1,0]
	v_pk_mul_f32 v[70:71], v[70:71], v[86:87] op_sel_hi:[1,0]
	v_pk_mul_f32 v[78:79], v[78:79], v[86:87] op_sel_hi:[1,0]
	v_pk_mul_f32 v[64:65], v[64:65], v[86:87] op_sel_hi:[1,0]
	v_pk_mul_f32 v[72:73], v[72:73], v[86:87] op_sel_hi:[1,0]
	v_mul_f32_e32 v93, 0xbfb8aa3b, v67
	v_mul_f32_e32 v86, 0xbfb8aa3b, v83
	v_mul_f32_e32 v87, 0xbfb8aa3b, v69
	v_mul_f32_e32 v88, 0xbfb8aa3b, v77
	v_mul_f32_e32 v89, 0xbfb8aa3b, v71
	v_mul_f32_e32 v90, 0xbfb8aa3b, v79
	v_mul_f32_e32 v91, 0xbfb8aa3b, v65
	v_mul_f32_e32 v92, 0xbfb8aa3b, v73
	v_exp_f32_e32 v93, v93
	v_exp_f32_e32 v86, v86
	v_exp_f32_e32 v87, v87
	v_exp_f32_e32 v88, v88
	v_exp_f32_e32 v89, v89
	v_exp_f32_e32 v90, v90
	v_exp_f32_e32 v91, v91
	v_exp_f32_e32 v92, v92
	v_add_f32_e32 v93, 1.0, v93
	v_add_f32_e32 v86, 1.0, v86
	v_add_f32_e32 v87, 1.0, v87
	v_add_f32_e32 v88, 1.0, v88
	v_add_f32_e32 v89, 1.0, v89
	v_add_f32_e32 v90, 1.0, v90
	v_add_f32_e32 v91, 1.0, v91
	v_add_f32_e32 v92, 1.0, v92
	v_rcp_f32_e32 v93, v93
	v_or_b32_e32 v75, 48, v142
	v_rcp_f32_e32 v86, v86
	v_rcp_f32_e32 v87, v87
	v_rcp_f32_e32 v88, v88
	v_rcp_f32_e32 v89, v89
	v_rcp_f32_e32 v90, v90
	v_rcp_f32_e32 v91, v91
	v_rcp_f32_e32 v92, v92
	v_mad_i64_i32 v[84:85], s[54:55], v75, s28, v[122:123]
	v_lshl_add_u64 v[84:85], v[84:85], 0, s[46:47]
	v_add_u32_e32 v74, 0x10080, v142
	v_lshl_add_u64 v[84:85], v[84:85], 0, v[80:81]
	v_mul_f32_e32 v67, v67, v93
	v_ashrrev_i32_e32 v75, 31, v74
	v_lshl_add_u64 v[84:85], v[84:85], 0, v[124:125]
	v_mul_f32_e32 v83, v83, v86
	v_mul_f32_e32 v69, v69, v87
	v_mul_f32_e32 v77, v77, v88
	v_mul_f32_e32 v71, v71, v89
	v_mul_f32_e32 v79, v79, v90
	v_mul_f32_e32 v65, v65, v91
	v_mul_f32_e32 v73, v73, v92
	v_mul_f32_e32 v67, v66, v67
	v_lshl_add_u64 v[74:75], v[74:75], 2, s[90:91]
	v_mul_f32_e32 v82, v82, v83
	v_mul_f32_e32 v68, v68, v69
	v_mul_f32_e32 v69, v76, v77
	v_mul_f32_e32 v70, v70, v71
	v_mul_f32_e32 v71, v78, v79
	v_mul_f32_e32 v76, v64, v65
	v_mul_f32_e32 v72, v72, v73
	v_cvt_pk_bf16_f32 v64, v82, v68
	v_cvt_pk_bf16_f32 v65, v69, v70
	v_cvt_pk_bf16_f32 v66, v71, v76
	v_cvt_pk_bf16_f32 v67, v72, v67
	global_store_dwordx4 v[84:85], v[64:67], off nt
	s_nop 0
	s_waitcnt vmcnt(7)
	v_fmamk_f32 v68, v246, 0x3a800000, v194
	v_mul_f32_e32 v69, 0x4b800000, v68
	v_cmp_gt_f32_e32 vcc, s19, v68
	v_mov_b32_e32 v65, v52
	v_mov_b32_e32 v52, v61
	v_cndmask_b32_e32 v68, v68, v69, vcc
	v_rsq_f32_e32 v68, v68
	v_mov_b32_e32 v61, v54
	v_mov_b32_e32 v54, v63
	v_mov_b32_e32 v63, v48
	v_mul_f32_e32 v69, 0x45800000, v68
	v_mov_b32_e32 v48, v57
	v_mov_b32_e32 v57, v50
	v_mov_b32_e32 v50, v59
	v_cndmask_b32_e32 v68, v68, v69, vcc
	v_mov_b32_e32 v64, v60
	v_mov_b32_e32 v60, v62
	v_mov_b32_e32 v62, v56
	v_mov_b32_e32 v56, v58
	v_pk_mul_f32 v[50:51], v[50:51], v[68:69] op_sel_hi:[1,0]
	v_pk_mul_f32 v[64:65], v[64:65], v[68:69] op_sel_hi:[1,0]
	v_pk_mul_f32 v[52:53], v[52:53], v[68:69] op_sel_hi:[1,0]
	v_pk_mul_f32 v[60:61], v[60:61], v[68:69] op_sel_hi:[1,0]
	v_pk_mul_f32 v[54:55], v[54:55], v[68:69] op_sel_hi:[1,0]
	v_pk_mul_f32 v[62:63], v[62:63], v[68:69] op_sel_hi:[1,0]
	v_pk_mul_f32 v[48:49], v[48:49], v[68:69] op_sel_hi:[1,0]
	v_pk_mul_f32 v[56:57], v[56:57], v[68:69] op_sel_hi:[1,0]
	v_mul_f32_e32 v75, 0xbfb8aa3b, v51
	v_mul_f32_e32 v68, 0xbfb8aa3b, v65
	v_mul_f32_e32 v69, 0xbfb8aa3b, v53
	v_mul_f32_e32 v70, 0xbfb8aa3b, v61
	v_mul_f32_e32 v71, 0xbfb8aa3b, v55
	v_mul_f32_e32 v72, 0xbfb8aa3b, v63
	v_mul_f32_e32 v73, 0xbfb8aa3b, v49
	v_mul_f32_e32 v74, 0xbfb8aa3b, v57
	v_exp_f32_e32 v75, v75
	v_exp_f32_e32 v68, v68
	v_exp_f32_e32 v69, v69
	v_exp_f32_e32 v70, v70
	v_exp_f32_e32 v71, v71
	v_exp_f32_e32 v72, v72
	v_exp_f32_e32 v73, v73
	v_exp_f32_e32 v74, v74
	v_add_f32_e32 v75, 1.0, v75
	v_add_f32_e32 v68, 1.0, v68
	v_add_f32_e32 v69, 1.0, v69
	v_add_f32_e32 v70, 1.0, v70
	v_add_f32_e32 v71, 1.0, v71
	v_add_f32_e32 v72, 1.0, v72
	v_add_f32_e32 v73, 1.0, v73
	v_add_f32_e32 v74, 1.0, v74
	v_rcp_f32_e32 v75, v75
	v_add_u32_e32 v59, 0x80, v142
	v_rcp_f32_e32 v68, v68
	v_rcp_f32_e32 v69, v69
	v_rcp_f32_e32 v70, v70
	v_rcp_f32_e32 v71, v71
	v_rcp_f32_e32 v72, v72
	v_rcp_f32_e32 v73, v73
	v_rcp_f32_e32 v74, v74
	v_mad_i64_i32 v[66:67], s[54:55], v59, s28, v[122:123]
	v_lshl_add_u64 v[66:67], v[66:67], 0, s[46:47]
	v_add_u32_e32 v58, 0x10090, v142
	v_lshl_add_u64 v[66:67], v[66:67], 0, v[80:81]
	v_mul_f32_e32 v51, v51, v75
	v_ashrrev_i32_e32 v59, 31, v58
	v_lshl_add_u64 v[66:67], v[66:67], 0, v[124:125]
	v_mul_f32_e32 v65, v65, v68
	v_mul_f32_e32 v53, v53, v69
	v_mul_f32_e32 v61, v61, v70
	v_mul_f32_e32 v55, v55, v71
	v_mul_f32_e32 v63, v63, v72
	v_mul_f32_e32 v49, v49, v73
	v_mul_f32_e32 v57, v57, v74
	v_mul_f32_e32 v51, v50, v51
	v_lshl_add_u64 v[58:59], v[58:59], 2, s[90:91]
	v_mul_f32_e32 v64, v64, v65
	v_mul_f32_e32 v52, v52, v53
	v_mul_f32_e32 v53, v60, v61
	v_mul_f32_e32 v54, v54, v55
	v_mul_f32_e32 v55, v62, v63
	v_mul_f32_e32 v60, v48, v49
	v_mul_f32_e32 v56, v56, v57
	v_cvt_pk_bf16_f32 v48, v64, v52
	v_cvt_pk_bf16_f32 v49, v53, v54
	v_cvt_pk_bf16_f32 v50, v55, v60
	v_cvt_pk_bf16_f32 v51, v56, v51
	global_store_dwordx4 v[66:67], v[48:51], off nt
	s_nop 0
	s_waitcnt vmcnt(7)
	v_fmamk_f32 v52, v247, 0x3a800000, v194
	v_mul_f32_e32 v53, 0x4b800000, v52
	v_cmp_gt_f32_e32 vcc, s19, v52
	v_mov_b32_e32 v49, v36
	v_mov_b32_e32 v36, v45
	v_cndmask_b32_e32 v52, v52, v53, vcc
	v_rsq_f32_e32 v52, v52
	v_mov_b32_e32 v45, v38
	v_mov_b32_e32 v38, v47
	v_mov_b32_e32 v47, v32
	v_mul_f32_e32 v53, 0x45800000, v52
	v_mov_b32_e32 v32, v41
	v_mov_b32_e32 v41, v34
	v_mov_b32_e32 v34, v43
	v_cndmask_b32_e32 v52, v52, v53, vcc
	v_mov_b32_e32 v48, v44
	v_mov_b32_e32 v44, v46
	v_mov_b32_e32 v46, v40
	v_mov_b32_e32 v40, v42
	v_pk_mul_f32 v[34:35], v[34:35], v[52:53] op_sel_hi:[1,0]
	v_pk_mul_f32 v[48:49], v[48:49], v[52:53] op_sel_hi:[1,0]
	v_pk_mul_f32 v[36:37], v[36:37], v[52:53] op_sel_hi:[1,0]
	v_pk_mul_f32 v[44:45], v[44:45], v[52:53] op_sel_hi:[1,0]
	v_pk_mul_f32 v[38:39], v[38:39], v[52:53] op_sel_hi:[1,0]
	v_pk_mul_f32 v[46:47], v[46:47], v[52:53] op_sel_hi:[1,0]
	v_pk_mul_f32 v[32:33], v[32:33], v[52:53] op_sel_hi:[1,0]
	v_pk_mul_f32 v[40:41], v[40:41], v[52:53] op_sel_hi:[1,0]
	v_mul_f32_e32 v59, 0xbfb8aa3b, v35
	v_mul_f32_e32 v52, 0xbfb8aa3b, v49
	v_mul_f32_e32 v53, 0xbfb8aa3b, v37
	v_mul_f32_e32 v54, 0xbfb8aa3b, v45
	v_mul_f32_e32 v55, 0xbfb8aa3b, v39
	v_mul_f32_e32 v56, 0xbfb8aa3b, v47
	v_mul_f32_e32 v57, 0xbfb8aa3b, v33
	v_mul_f32_e32 v58, 0xbfb8aa3b, v41
	v_exp_f32_e32 v59, v59
	v_exp_f32_e32 v52, v52
	v_exp_f32_e32 v53, v53
	v_exp_f32_e32 v54, v54
	v_exp_f32_e32 v55, v55
	v_exp_f32_e32 v56, v56
	v_exp_f32_e32 v57, v57
	v_exp_f32_e32 v58, v58
	v_add_f32_e32 v59, 1.0, v59
	v_add_f32_e32 v52, 1.0, v52
	v_add_f32_e32 v53, 1.0, v53
	v_add_f32_e32 v54, 1.0, v54
	v_add_f32_e32 v55, 1.0, v55
	v_add_f32_e32 v56, 1.0, v56
	v_add_f32_e32 v57, 1.0, v57
	v_add_f32_e32 v58, 1.0, v58
	v_rcp_f32_e32 v59, v59
	v_add_u32_e32 v43, 0x90, v142
	v_rcp_f32_e32 v52, v52
	v_rcp_f32_e32 v53, v53
	v_rcp_f32_e32 v54, v54
	v_rcp_f32_e32 v55, v55
	v_rcp_f32_e32 v56, v56
	v_rcp_f32_e32 v57, v57
	v_rcp_f32_e32 v58, v58
	v_mad_i64_i32 v[50:51], s[54:55], v43, s28, v[122:123]
	v_lshl_add_u64 v[50:51], v[50:51], 0, s[46:47]
	v_add_u32_e32 v42, 0x100a0, v142
	v_lshl_add_u64 v[50:51], v[50:51], 0, v[80:81]
	v_mul_f32_e32 v35, v35, v59
	v_ashrrev_i32_e32 v43, 31, v42
	v_lshl_add_u64 v[50:51], v[50:51], 0, v[124:125]
	v_mul_f32_e32 v49, v49, v52
	v_mul_f32_e32 v37, v37, v53
	v_mul_f32_e32 v45, v45, v54
	v_mul_f32_e32 v39, v39, v55
	v_mul_f32_e32 v47, v47, v56
	v_mul_f32_e32 v33, v33, v57
	v_mul_f32_e32 v41, v41, v58
	v_mul_f32_e32 v35, v34, v35
	v_lshl_add_u64 v[42:43], v[42:43], 2, s[90:91]
	v_mul_f32_e32 v48, v48, v49
	v_mul_f32_e32 v36, v36, v37
	v_mul_f32_e32 v37, v44, v45
	v_mul_f32_e32 v38, v38, v39
	v_mul_f32_e32 v39, v46, v47
	v_mul_f32_e32 v44, v32, v33
	v_mul_f32_e32 v40, v40, v41
	v_cvt_pk_bf16_f32 v32, v48, v36
	v_cvt_pk_bf16_f32 v33, v37, v38
	v_cvt_pk_bf16_f32 v34, v39, v44
	v_cvt_pk_bf16_f32 v35, v40, v35
	global_store_dwordx4 v[50:51], v[32:35], off nt
	s_nop 0
	s_waitcnt vmcnt(7)
	v_fmamk_f32 v36, v248, 0x3a800000, v194
	v_mul_f32_e32 v37, 0x4b800000, v36
	v_cmp_gt_f32_e32 vcc, s19, v36
	v_mov_b32_e32 v33, v20
	v_mov_b32_e32 v20, v29
	v_cndmask_b32_e32 v36, v36, v37, vcc
	v_rsq_f32_e32 v36, v36
	v_mov_b32_e32 v29, v22
	v_mov_b32_e32 v22, v31
	v_mov_b32_e32 v31, v16
	v_mul_f32_e32 v37, 0x45800000, v36
	v_mov_b32_e32 v16, v25
	v_mov_b32_e32 v25, v18
	v_mov_b32_e32 v18, v27
	v_cndmask_b32_e32 v36, v36, v37, vcc
	v_mov_b32_e32 v32, v28
	v_mov_b32_e32 v28, v30
	v_mov_b32_e32 v30, v24
	v_mov_b32_e32 v24, v26
	v_pk_mul_f32 v[18:19], v[18:19], v[36:37] op_sel_hi:[1,0]
	v_pk_mul_f32 v[32:33], v[32:33], v[36:37] op_sel_hi:[1,0]
	v_pk_mul_f32 v[20:21], v[20:21], v[36:37] op_sel_hi:[1,0]
	v_pk_mul_f32 v[28:29], v[28:29], v[36:37] op_sel_hi:[1,0]
	v_pk_mul_f32 v[22:23], v[22:23], v[36:37] op_sel_hi:[1,0]
	v_pk_mul_f32 v[30:31], v[30:31], v[36:37] op_sel_hi:[1,0]
	v_pk_mul_f32 v[16:17], v[16:17], v[36:37] op_sel_hi:[1,0]
	v_pk_mul_f32 v[24:25], v[24:25], v[36:37] op_sel_hi:[1,0]
	v_mul_f32_e32 v43, 0xbfb8aa3b, v19
	v_mul_f32_e32 v36, 0xbfb8aa3b, v33
	v_mul_f32_e32 v37, 0xbfb8aa3b, v21
	v_mul_f32_e32 v38, 0xbfb8aa3b, v29
	v_mul_f32_e32 v39, 0xbfb8aa3b, v23
	v_mul_f32_e32 v40, 0xbfb8aa3b, v31
	v_mul_f32_e32 v41, 0xbfb8aa3b, v17
	v_mul_f32_e32 v42, 0xbfb8aa3b, v25
	v_exp_f32_e32 v43, v43
	v_exp_f32_e32 v36, v36
	v_exp_f32_e32 v37, v37
	v_exp_f32_e32 v38, v38
	v_exp_f32_e32 v39, v39
	v_exp_f32_e32 v40, v40
	v_exp_f32_e32 v41, v41
	v_exp_f32_e32 v42, v42
	v_add_f32_e32 v43, 1.0, v43
	v_add_f32_e32 v36, 1.0, v36
	v_add_f32_e32 v37, 1.0, v37
	v_add_f32_e32 v38, 1.0, v38
	v_add_f32_e32 v39, 1.0, v39
	v_add_f32_e32 v40, 1.0, v40
	v_add_f32_e32 v41, 1.0, v41
	v_add_f32_e32 v42, 1.0, v42
	v_rcp_f32_e32 v43, v43
	v_add_u32_e32 v27, 0xa0, v142
	v_rcp_f32_e32 v36, v36
	v_rcp_f32_e32 v37, v37
	v_rcp_f32_e32 v38, v38
	v_rcp_f32_e32 v39, v39
	v_rcp_f32_e32 v40, v40
	v_rcp_f32_e32 v41, v41
	v_rcp_f32_e32 v42, v42
	v_mad_i64_i32 v[34:35], s[54:55], v27, s28, v[122:123]
	v_lshl_add_u64 v[34:35], v[34:35], 0, s[46:47]
	v_add_u32_e32 v26, 0x100b0, v142
	v_lshl_add_u64 v[34:35], v[34:35], 0, v[80:81]
	v_mul_f32_e32 v19, v19, v43
	v_ashrrev_i32_e32 v27, 31, v26
	v_lshl_add_u64 v[34:35], v[34:35], 0, v[124:125]
	v_mul_f32_e32 v33, v33, v36
	v_mul_f32_e32 v21, v21, v37
	v_mul_f32_e32 v29, v29, v38
	v_mul_f32_e32 v23, v23, v39
	v_mul_f32_e32 v31, v31, v40
	v_mul_f32_e32 v17, v17, v41
	v_mul_f32_e32 v25, v25, v42
	v_mul_f32_e32 v19, v18, v19
	v_lshl_add_u64 v[26:27], v[26:27], 2, s[90:91]
	v_mul_f32_e32 v32, v32, v33
	v_mul_f32_e32 v20, v20, v21
	v_mul_f32_e32 v21, v28, v29
	v_mul_f32_e32 v22, v22, v23
	v_mul_f32_e32 v23, v30, v31
	v_mul_f32_e32 v28, v16, v17
	v_mul_f32_e32 v24, v24, v25
	v_cvt_pk_bf16_f32 v16, v32, v20
	v_cvt_pk_bf16_f32 v17, v21, v22
	v_cvt_pk_bf16_f32 v18, v23, v28
	v_cvt_pk_bf16_f32 v19, v24, v19
	global_store_dwordx4 v[34:35], v[16:19], off nt
	s_nop 0
	s_andn2_b64 vcc, exec, s[44:45]
	v_mov_b32_e32 v16, v12
	v_mov_b32_e32 v12, v14
	v_mov_b32_e32 v14, v4
	v_mov_b32_e32 v4, v6
	v_add_u32_e32 v6, 0xb0, v142
	v_mov_b32_e32 v17, v8
	v_mov_b32_e32 v8, v13
	v_mov_b32_e32 v13, v10
	v_mov_b32_e32 v10, v15
	v_mov_b32_e32 v15, v0
	v_mov_b32_e32 v0, v5
	v_mov_b32_e32 v5, v2
	v_mov_b32_e32 v2, v7
	v_mad_i64_i32 v[6:7], s[54:55], v6, s28, v[122:123]
	v_lshl_add_u64 v[6:7], v[6:7], 0, s[46:47]
	v_lshl_add_u64 v[6:7], v[6:7], 0, v[80:81]
	v_lshl_add_u64 v[6:7], v[6:7], 0, v[124:125]
	s_mov_b64 s[44:45], -1
	s_waitcnt vmcnt(7)
	v_fmamk_f32 v18, v249, 0x3a800000, v194
	v_mul_f32_e32 v19, 0x4b800000, v18
	v_cmp_gt_f32_e64 s[46:47], s19, v18
	s_nop 1
	v_cndmask_b32_e64 v18, v18, v19, s[46:47]
	v_rsq_f32_e32 v18, v18
	s_nop 0
	v_mul_f32_e32 v19, 0x45800000, v18
	v_cndmask_b32_e64 v18, v18, v19, s[46:47]
	v_pk_mul_f32 v[2:3], v[2:3], v[18:19] op_sel_hi:[1,0]
	v_pk_mul_f32 v[16:17], v[16:17], v[18:19] op_sel_hi:[1,0]
	v_pk_mul_f32 v[8:9], v[8:9], v[18:19] op_sel_hi:[1,0]
	v_pk_mul_f32 v[12:13], v[12:13], v[18:19] op_sel_hi:[1,0]
	v_pk_mul_f32 v[10:11], v[10:11], v[18:19] op_sel_hi:[1,0]
	v_pk_mul_f32 v[14:15], v[14:15], v[18:19] op_sel_hi:[1,0]
	v_pk_mul_f32 v[0:1], v[0:1], v[18:19] op_sel_hi:[1,0]
	v_pk_mul_f32 v[4:5], v[4:5], v[18:19] op_sel_hi:[1,0]
	v_mul_f32_e32 v25, 0xbfb8aa3b, v3
	v_mul_f32_e32 v18, 0xbfb8aa3b, v17
	v_mul_f32_e32 v19, 0xbfb8aa3b, v9
	v_mul_f32_e32 v20, 0xbfb8aa3b, v13
	v_mul_f32_e32 v21, 0xbfb8aa3b, v11
	v_mul_f32_e32 v22, 0xbfb8aa3b, v15
	v_mul_f32_e32 v23, 0xbfb8aa3b, v1
	v_mul_f32_e32 v24, 0xbfb8aa3b, v5
	v_exp_f32_e32 v25, v25
	v_exp_f32_e32 v18, v18
	v_exp_f32_e32 v19, v19
	v_exp_f32_e32 v20, v20
	v_exp_f32_e32 v21, v21
	v_exp_f32_e32 v22, v22
	v_exp_f32_e32 v23, v23
	v_exp_f32_e32 v24, v24
	v_add_f32_e32 v25, 1.0, v25
	v_add_f32_e32 v18, 1.0, v18
	v_add_f32_e32 v19, 1.0, v19
	v_add_f32_e32 v20, 1.0, v20
	v_add_f32_e32 v21, 1.0, v21
	v_add_f32_e32 v22, 1.0, v22
	v_add_f32_e32 v23, 1.0, v23
	v_add_f32_e32 v24, 1.0, v24
	v_rcp_f32_e32 v25, v25
	v_rcp_f32_e32 v18, v18
	v_rcp_f32_e32 v19, v19
	v_rcp_f32_e32 v20, v20
	v_rcp_f32_e32 v21, v21
	v_rcp_f32_e32 v22, v22
	v_rcp_f32_e32 v23, v23
	v_rcp_f32_e32 v24, v24
	v_mul_f32_e32 v3, v3, v25
	v_mul_f32_e32 v17, v17, v18
	v_mul_f32_e32 v9, v9, v19
	v_mul_f32_e32 v13, v13, v20
	v_mul_f32_e32 v11, v11, v21
	v_mul_f32_e32 v15, v15, v22
	v_mul_f32_e32 v1, v1, v23
	v_mul_f32_e32 v5, v5, v24
	v_mul_f32_e32 v3, v2, v3
	v_mul_f32_e32 v16, v16, v17
	v_mul_f32_e32 v8, v8, v9
	v_mul_f32_e32 v9, v12, v13
	v_mul_f32_e32 v10, v10, v11
	v_mul_f32_e32 v11, v14, v15
	v_mul_f32_e32 v12, v0, v1
	v_mul_f32_e32 v4, v4, v5
	v_cvt_pk_bf16_f32 v0, v16, v8
	v_cvt_pk_bf16_f32 v1, v9, v10
	v_cvt_pk_bf16_f32 v2, v11, v12
	v_cvt_pk_bf16_f32 v3, v4, v3
	global_store_dwordx4 v[6:7], v[0:3], off nt
	s_cbranch_vccnz .LBB0_223
	s_andn2_b64 vcc, exec, s[0:1]
	s_cbranch_vccnz .LBB0_222
	s_barrier
	s_branch .LBB0_222

.LBB0_677:
	s_add_u32 s48, s46, 0xfffc0080
	s_addc_u32 s49, s47, -1
	s_add_i32 s61, 16, 0x10000
	s_cmp_eq_u32 s60, 12
	s_cselect_b32 s51, s15, s49
	s_cselect_b32 s50, s54, s48
	v_add_u32_e32 v80, s61, v146
	s_cselect_b32 s49, s11, s57
	s_cselect_b32 s48, s55, s56
	s_add_i32 s74, 16, 0x14000
	ds_read_b128 v[142:145], v80
	ds_read_b128 v[148:151], v80 offset:1024
	ds_read_b128 v[160:163], v80 offset:2048
	ds_read_b128 v[164:167], v80 offset:3072
	v_add_u32_e32 v80, s74, v146
	ds_read_b128 v[168:171], v80
	ds_read_b128 v[172:175], v80 offset:1024
	ds_read_b128 v[176:179], v80 offset:2048
	ds_read_b128 v[180:183], v80 offset:3072
	v_lshl_add_u64 v[208:209], s[46:47], 0, v[138:139]
	s_add_i32 m0, s13, 0xc000
	ds_read_b128 v[184:187], v147
	ds_read_b128 v[188:191], v147 offset:1024
	ds_read_b128 v[204:207], v147 offset:2048
	ds_read_b128 v[214:217], v147 offset:3072
	ds_read_b128 v[218:221], v147 offset:4096
	ds_read_b128 v[222:225], v147 offset:5120
	ds_read_b128 v[226:229], v147 offset:6144
	ds_read_b128 v[230:233], v147 offset:7168
	global_load_lds_dwordx4 v[208:209], off
	v_lshl_add_u64 v[208:209], s[46:47], 0, v[140:141]
	s_add_i32 m0, s13, 0xe000
	s_nop 0
	global_load_lds_dwordx4 v[208:209], off
	s_waitcnt vmcnt(8)
	s_waitcnt lgkmcnt(0)
	s_barrier
	s_setprio 1
	s_waitcnt lgkmcnt(0)
	v_mfma_f32_16x16x32_bf16 v[126:129], v[142:145], v[184:187], v[126:129]
	v_mfma_f32_16x16x32_bf16 v[118:121], v[160:163], v[184:187], v[118:121]
	v_mfma_f32_16x16x32_bf16 v[110:113], v[142:145], v[204:207], v[110:113]
	v_mfma_f32_16x16x32_bf16 v[102:105], v[160:163], v[204:207], v[102:105]
	v_mfma_f32_16x16x32_bf16 v[94:97], v[142:145], v[218:221], v[94:97]
	v_mfma_f32_16x16x32_bf16 v[86:89], v[160:163], v[218:221], v[86:89]
	v_mfma_f32_16x16x32_bf16 v[76:79], v[142:145], v[226:229], v[76:79]
	v_mfma_f32_16x16x32_bf16 v[68:71], v[160:163], v[226:229], v[68:71]
	v_mfma_f32_16x16x32_bf16 v[126:129], v[148:151], v[188:191], v[126:129]
	v_mfma_f32_16x16x32_bf16 v[118:121], v[164:167], v[188:191], v[118:121]
	v_mfma_f32_16x16x32_bf16 v[110:113], v[148:151], v[214:217], v[110:113]
	v_mfma_f32_16x16x32_bf16 v[102:105], v[164:167], v[214:217], v[102:105]
	v_mfma_f32_16x16x32_bf16 v[94:97], v[148:151], v[222:225], v[94:97]
	v_mfma_f32_16x16x32_bf16 v[86:89], v[164:167], v[222:225], v[86:89]
	v_mfma_f32_16x16x32_bf16 v[76:79], v[148:151], v[230:233], v[76:79]
	v_mfma_f32_16x16x32_bf16 v[68:71], v[164:167], v[230:233], v[68:71]
	s_setprio 0
	s_setprio 1
	v_mfma_f32_16x16x32_bf16 v[122:125], v[168:171], v[184:187], v[122:125]
	v_mfma_f32_16x16x32_bf16 v[114:117], v[176:179], v[184:187], v[114:117]
	v_mfma_f32_16x16x32_bf16 v[106:109], v[168:171], v[204:207], v[106:109]
	v_mfma_f32_16x16x32_bf16 v[98:101], v[176:179], v[204:207], v[98:101]
	v_mfma_f32_16x16x32_bf16 v[90:93], v[168:171], v[218:221], v[90:93]
	v_mfma_f32_16x16x32_bf16 v[82:85], v[176:179], v[218:221], v[82:85]
	v_mfma_f32_16x16x32_bf16 v[72:75], v[168:171], v[226:229], v[72:75]
	v_mfma_f32_16x16x32_bf16 v[64:67], v[176:179], v[226:229], v[64:67]
	v_mfma_f32_16x16x32_bf16 v[122:125], v[172:175], v[188:191], v[122:125]
	v_mfma_f32_16x16x32_bf16 v[114:117], v[180:183], v[188:191], v[114:117]
	v_mfma_f32_16x16x32_bf16 v[106:109], v[172:175], v[214:217], v[106:109]
	v_mfma_f32_16x16x32_bf16 v[98:101], v[180:183], v[214:217], v[98:101]
	v_mfma_f32_16x16x32_bf16 v[90:93], v[172:175], v[222:225], v[90:93]
	v_mfma_f32_16x16x32_bf16 v[82:85], v[180:183], v[222:225], v[82:85]
	v_mfma_f32_16x16x32_bf16 v[72:75], v[172:175], v[230:233], v[72:75]
	v_mfma_f32_16x16x32_bf16 v[64:67], v[180:183], v[230:233], v[64:67]
	s_setprio 0
	s_barrier
	s_add_i32 s61, s61, s4
	v_lshl_add_u64 v[208:209], s[48:49], 0, v[134:135]
	s_mov_b32 m0, s61
	ds_read_b128 v[184:187], v147 offset:16384
	ds_read_b128 v[188:191], v147 offset:17408
	ds_read_b128 v[204:207], v147 offset:18432
	ds_read_b128 v[214:217], v147 offset:19456
	ds_read_b128 v[218:221], v147 offset:20480
	ds_read_b128 v[222:225], v147 offset:21504
	ds_read_b128 v[226:229], v147 offset:22528
	ds_read_b128 v[230:233], v147 offset:23552
	global_load_lds_dwordx4 v[208:209], off
	s_add_i32 m0, s61, 0x2000
	s_add_u32 s66, s48, 0x40000
	v_lshl_add_u64 v[234:235], s[48:49], 0, v[130:131]
	s_addc_u32 s67, s49, 0
	s_add_i32 s61, s74, s4
	global_load_lds_dwordx4 v[234:235], off
	v_lshl_add_u64 v[236:237], s[66:67], 0, v[134:135]
	s_mov_b32 m0, s61
	v_lshl_add_u64 v[238:239], s[50:51], 0, v[132:133]
	global_load_lds_dwordx4 v[236:237], off
	v_lshl_add_u64 v[236:237], s[66:67], 0, v[130:131]
	s_add_i32 m0, s61, 0x2000
	s_nop 0
	global_load_lds_dwordx4 v[236:237], off
	v_lshl_add_u64 v[236:237], s[50:51], 0, v[136:137]
	s_mov_b32 m0, s13
	s_nop 0
	global_load_lds_dwordx4 v[236:237], off
	s_mov_b32 m0, s25
	s_nop 0
	global_load_lds_dwordx4 v[238:239], off
	s_waitcnt vmcnt(8)
	s_waitcnt lgkmcnt(0)
	s_barrier
	s_setprio 1
	s_waitcnt lgkmcnt(0)
	v_mfma_f32_16x16x32_bf16 v[60:63], v[142:145], v[184:187], v[60:63]
	v_mfma_f32_16x16x32_bf16 v[52:55], v[160:163], v[184:187], v[52:55]
	v_mfma_f32_16x16x32_bf16 v[44:47], v[142:145], v[204:207], v[44:47]
	v_mfma_f32_16x16x32_bf16 v[36:39], v[160:163], v[204:207], v[36:39]
	v_mfma_f32_16x16x32_bf16 v[28:31], v[142:145], v[218:221], v[28:31]
	v_mfma_f32_16x16x32_bf16 v[20:23], v[160:163], v[218:221], v[20:23]
	v_mfma_f32_16x16x32_bf16 v[12:15], v[142:145], v[226:229], v[12:15]
	v_mfma_f32_16x16x32_bf16 v[4:7], v[160:163], v[226:229], v[4:7]
	v_mfma_f32_16x16x32_bf16 v[60:63], v[148:151], v[188:191], v[60:63]
	v_mfma_f32_16x16x32_bf16 v[52:55], v[164:167], v[188:191], v[52:55]
	v_mfma_f32_16x16x32_bf16 v[44:47], v[148:151], v[214:217], v[44:47]
	v_mfma_f32_16x16x32_bf16 v[36:39], v[164:167], v[214:217], v[36:39]
	v_mfma_f32_16x16x32_bf16 v[28:31], v[148:151], v[222:225], v[28:31]
	v_mfma_f32_16x16x32_bf16 v[20:23], v[164:167], v[222:225], v[20:23]
	v_mfma_f32_16x16x32_bf16 v[12:15], v[148:151], v[230:233], v[12:15]
	v_mfma_f32_16x16x32_bf16 v[4:7], v[164:167], v[230:233], v[4:7]
	s_setprio 0
	s_setprio 1
	v_mfma_f32_16x16x32_bf16 v[56:59], v[168:171], v[184:187], v[56:59]
	v_mfma_f32_16x16x32_bf16 v[48:51], v[176:179], v[184:187], v[48:51]
	v_mfma_f32_16x16x32_bf16 v[40:43], v[168:171], v[204:207], v[40:43]
	v_mfma_f32_16x16x32_bf16 v[32:35], v[176:179], v[204:207], v[32:35]
	v_mfma_f32_16x16x32_bf16 v[24:27], v[168:171], v[218:221], v[24:27]
	v_mfma_f32_16x16x32_bf16 v[16:19], v[176:179], v[218:221], v[16:19]
	v_mfma_f32_16x16x32_bf16 v[8:11], v[168:171], v[226:229], v[8:11]
	v_mfma_f32_16x16x32_bf16 v[0:3], v[176:179], v[226:229], v[0:3]
	v_mfma_f32_16x16x32_bf16 v[56:59], v[172:175], v[188:191], v[56:59]
	v_mfma_f32_16x16x32_bf16 v[48:51], v[180:183], v[188:191], v[48:51]
	v_mfma_f32_16x16x32_bf16 v[40:43], v[172:175], v[214:217], v[40:43]
	v_mfma_f32_16x16x32_bf16 v[32:35], v[180:183], v[214:217], v[32:35]
	v_mfma_f32_16x16x32_bf16 v[24:27], v[172:175], v[222:225], v[24:27]
	v_mfma_f32_16x16x32_bf16 v[16:19], v[180:183], v[222:225], v[16:19]
	v_mfma_f32_16x16x32_bf16 v[8:11], v[172:175], v[230:233], v[8:11]
	v_mfma_f32_16x16x32_bf16 v[0:3], v[180:183], v[230:233], v[0:3]
	s_setprio 0
	s_barrier
	s_add_i32 s61, 16, 0x18000
	v_add_u32_e32 v80, s61, v146
	s_add_i32 s66, 16, 0x1c000
	ds_read_b128 v[142:145], v80
	ds_read_b128 v[148:151], v80 offset:1024
	ds_read_b128 v[160:163], v80 offset:2048
	ds_read_b128 v[164:167], v80 offset:3072
	v_add_u32_e32 v80, s66, v146
	ds_read_b128 v[168:171], v80
	ds_read_b128 v[172:175], v80 offset:1024
	ds_read_b128 v[176:179], v80 offset:2048
	ds_read_b128 v[180:183], v80 offset:3072
	s_add_u32 s50, s50, 0x40000
	s_addc_u32 s51, s51, 0
	s_mov_b32 m0, s30
	v_lshl_add_u64 v[240:241], s[50:51], 0, v[136:137]
	ds_read_b128 v[184:187], v147 offset:32768
	ds_read_b128 v[188:191], v147 offset:33792
	ds_read_b128 v[204:207], v147 offset:34816
	ds_read_b128 v[214:217], v147 offset:35840
	ds_read_b128 v[218:221], v147 offset:36864
	ds_read_b128 v[222:225], v147 offset:37888
	ds_read_b128 v[226:229], v147 offset:38912
	ds_read_b128 v[230:233], v147 offset:39936
	global_load_lds_dwordx4 v[240:241], off
	v_lshl_add_u64 v[240:241], s[50:51], 0, v[132:133]
	s_mov_b32 m0, s33
	s_nop 0
	global_load_lds_dwordx4 v[240:241], off
	s_waitcnt vmcnt(8)
	s_waitcnt lgkmcnt(0)
	s_barrier
	s_setprio 1
	s_waitcnt lgkmcnt(0)
	v_mfma_f32_16x16x32_bf16 v[126:129], v[142:145], v[184:187], v[126:129]
	v_mfma_f32_16x16x32_bf16 v[118:121], v[160:163], v[184:187], v[118:121]
	v_mfma_f32_16x16x32_bf16 v[110:113], v[142:145], v[204:207], v[110:113]
	v_mfma_f32_16x16x32_bf16 v[102:105], v[160:163], v[204:207], v[102:105]
	v_mfma_f32_16x16x32_bf16 v[94:97], v[142:145], v[218:221], v[94:97]
	v_mfma_f32_16x16x32_bf16 v[86:89], v[160:163], v[218:221], v[86:89]
	v_mfma_f32_16x16x32_bf16 v[76:79], v[142:145], v[226:229], v[76:79]
	v_mfma_f32_16x16x32_bf16 v[68:71], v[160:163], v[226:229], v[68:71]
	v_mfma_f32_16x16x32_bf16 v[126:129], v[148:151], v[188:191], v[126:129]
	v_mfma_f32_16x16x32_bf16 v[118:121], v[164:167], v[188:191], v[118:121]
	v_mfma_f32_16x16x32_bf16 v[110:113], v[148:151], v[214:217], v[110:113]
	v_mfma_f32_16x16x32_bf16 v[102:105], v[164:167], v[214:217], v[102:105]
	v_mfma_f32_16x16x32_bf16 v[94:97], v[148:151], v[222:225], v[94:97]
	v_mfma_f32_16x16x32_bf16 v[86:89], v[164:167], v[222:225], v[86:89]
	v_mfma_f32_16x16x32_bf16 v[76:79], v[148:151], v[230:233], v[76:79]
	v_mfma_f32_16x16x32_bf16 v[68:71], v[164:167], v[230:233], v[68:71]
	s_setprio 0
	s_setprio 1
	v_mfma_f32_16x16x32_bf16 v[122:125], v[168:171], v[184:187], v[122:125]
	v_mfma_f32_16x16x32_bf16 v[114:117], v[176:179], v[184:187], v[114:117]
	v_mfma_f32_16x16x32_bf16 v[106:109], v[168:171], v[204:207], v[106:109]
	v_mfma_f32_16x16x32_bf16 v[98:101], v[176:179], v[204:207], v[98:101]
	v_mfma_f32_16x16x32_bf16 v[90:93], v[168:171], v[218:221], v[90:93]
	v_mfma_f32_16x16x32_bf16 v[82:85], v[176:179], v[218:221], v[82:85]
	v_mfma_f32_16x16x32_bf16 v[72:75], v[168:171], v[226:229], v[72:75]
	v_mfma_f32_16x16x32_bf16 v[64:67], v[176:179], v[226:229], v[64:67]
	v_mfma_f32_16x16x32_bf16 v[122:125], v[172:175], v[188:191], v[122:125]
	v_mfma_f32_16x16x32_bf16 v[114:117], v[180:183], v[188:191], v[114:117]
	v_mfma_f32_16x16x32_bf16 v[106:109], v[172:175], v[214:217], v[106:109]
	v_mfma_f32_16x16x32_bf16 v[98:101], v[180:183], v[214:217], v[98:101]
	v_mfma_f32_16x16x32_bf16 v[90:93], v[172:175], v[222:225], v[90:93]
	v_mfma_f32_16x16x32_bf16 v[82:85], v[180:183], v[222:225], v[82:85]
	v_mfma_f32_16x16x32_bf16 v[72:75], v[172:175], v[230:233], v[72:75]
	v_mfma_f32_16x16x32_bf16 v[64:67], v[180:183], v[230:233], v[64:67]
	s_setprio 0
	s_barrier
	s_add_i32 s50, s61, s4
	v_lshl_add_u64 v[208:209], v[208:209], 0, s[20:21]
	s_mov_b32 m0, s50
	ds_read_b128 v[184:187], v147 offset:49152
	ds_read_b128 v[188:191], v147 offset:50176
	ds_read_b128 v[204:207], v147 offset:51200
	ds_read_b128 v[214:217], v147 offset:52224
	ds_read_b128 v[218:221], v147 offset:53248
	ds_read_b128 v[222:225], v147 offset:54272
	ds_read_b128 v[226:229], v147 offset:55296
	ds_read_b128 v[230:233], v147 offset:56320
	global_load_lds_dwordx4 v[208:209], off
	s_add_i32 m0, s50, 0x2000
	s_add_u32 s48, s48, 0x40080
	v_lshl_add_u64 v[208:209], v[234:235], 0, s[20:21]
	s_addc_u32 s49, s49, 0
	s_add_i32 s50, s66, s4
	global_load_lds_dwordx4 v[208:209], off
	v_lshl_add_u64 v[208:209], s[48:49], 0, v[134:135]
	s_mov_b32 m0, s50
	s_nop 0
	global_load_lds_dwordx4 v[208:209], off
	v_lshl_add_u64 v[208:209], s[48:49], 0, v[130:131]
	s_add_i32 m0, s50, 0x2000
	s_nop 0
	global_load_lds_dwordx4 v[208:209], off
	v_lshl_add_u64 v[208:209], v[236:237], 0, s[20:21]
	s_mov_b32 m0, s34
	s_nop 0
	global_load_lds_dwordx4 v[208:209], off
	v_lshl_add_u64 v[208:209], v[238:239], 0, s[20:21]
	s_mov_b32 m0, s36
	s_nop 0
	global_load_lds_dwordx4 v[208:209], off
	s_waitcnt vmcnt(8)
	s_waitcnt lgkmcnt(0)
	s_barrier
	s_setprio 1
	s_waitcnt lgkmcnt(0)
	v_mfma_f32_16x16x32_bf16 v[60:63], v[142:145], v[184:187], v[60:63]
	v_mfma_f32_16x16x32_bf16 v[52:55], v[160:163], v[184:187], v[52:55]
	v_mfma_f32_16x16x32_bf16 v[44:47], v[142:145], v[204:207], v[44:47]
	v_mfma_f32_16x16x32_bf16 v[36:39], v[160:163], v[204:207], v[36:39]
	v_mfma_f32_16x16x32_bf16 v[28:31], v[142:145], v[218:221], v[28:31]
	v_mfma_f32_16x16x32_bf16 v[20:23], v[160:163], v[218:221], v[20:23]
	v_mfma_f32_16x16x32_bf16 v[12:15], v[142:145], v[226:229], v[12:15]
	v_mfma_f32_16x16x32_bf16 v[4:7], v[160:163], v[226:229], v[4:7]
	v_mfma_f32_16x16x32_bf16 v[60:63], v[148:151], v[188:191], v[60:63]
	v_mfma_f32_16x16x32_bf16 v[52:55], v[164:167], v[188:191], v[52:55]
	v_mfma_f32_16x16x32_bf16 v[44:47], v[148:151], v[214:217], v[44:47]
	v_mfma_f32_16x16x32_bf16 v[36:39], v[164:167], v[214:217], v[36:39]
	v_mfma_f32_16x16x32_bf16 v[28:31], v[148:151], v[222:225], v[28:31]
	v_mfma_f32_16x16x32_bf16 v[20:23], v[164:167], v[222:225], v[20:23]
	v_mfma_f32_16x16x32_bf16 v[12:15], v[148:151], v[230:233], v[12:15]
	v_mfma_f32_16x16x32_bf16 v[4:7], v[164:167], v[230:233], v[4:7]
	s_setprio 0
	s_setprio 1
	v_mfma_f32_16x16x32_bf16 v[56:59], v[168:171], v[184:187], v[56:59]
	v_mfma_f32_16x16x32_bf16 v[48:51], v[176:179], v[184:187], v[48:51]
	v_mfma_f32_16x16x32_bf16 v[40:43], v[168:171], v[204:207], v[40:43]
	v_mfma_f32_16x16x32_bf16 v[32:35], v[176:179], v[204:207], v[32:35]
	v_mfma_f32_16x16x32_bf16 v[24:27], v[168:171], v[218:221], v[24:27]
	v_mfma_f32_16x16x32_bf16 v[16:19], v[176:179], v[218:221], v[16:19]
	v_mfma_f32_16x16x32_bf16 v[8:11], v[168:171], v[226:229], v[8:11]
	v_mfma_f32_16x16x32_bf16 v[0:3], v[176:179], v[226:229], v[0:3]
	v_mfma_f32_16x16x32_bf16 v[56:59], v[172:175], v[188:191], v[56:59]
	v_mfma_f32_16x16x32_bf16 v[48:51], v[180:183], v[188:191], v[48:51]
	v_mfma_f32_16x16x32_bf16 v[40:43], v[172:175], v[214:217], v[40:43]
	v_mfma_f32_16x16x32_bf16 v[32:35], v[180:183], v[214:217], v[32:35]
	v_mfma_f32_16x16x32_bf16 v[24:27], v[172:175], v[222:225], v[24:27]
	v_mfma_f32_16x16x32_bf16 v[16:19], v[180:183], v[222:225], v[16:19]
	v_mfma_f32_16x16x32_bf16 v[8:11], v[172:175], v[230:233], v[8:11]
	v_mfma_f32_16x16x32_bf16 v[0:3], v[180:183], v[230:233], v[0:3]
	s_setprio 0
	s_barrier
	s_add_i32 s60, s60, 2
	s_add_u32 s46, s46, 0x100
	s_addc_u32 s47, s47, 0
	s_add_u32 s56, s56, 0x100
	s_addc_u32 s57, s57, 0
	s_cmp_gt_u32 s60, 13
	s_cbranch_scc0 .LBB0_677
	v_mov_b32_e32 v150, v192
	s_lshl_b32 s11, s53, 8
	v_mov_b32_e32 v148, v122
	v_ashrrev_i32_e32 v80, 2, v150
	v_and_b32_e32 v80, 0xffffffc0, v80
	v_and_or_b32 v142, v150, 15, s11
	v_add_u32_e32 v142, v142, v80
	v_ashrrev_i32_e32 v143, 31, v142
	v_lshl_add_u64 v[144:145], v[142:143], 2, s[90:91]
	global_load_dword v242, v[144:145], off
	global_load_dword v243, v[144:145], off offset:64
	global_load_dword v244, v[144:145], off offset:128
	global_load_dword v245, v[144:145], off offset:192
	global_load_dword v246, v[144:145], off offset:512
	global_load_dword v247, v[144:145], off offset:576
	global_load_dword v248, v[144:145], off offset:640
	global_load_dword v249, v[144:145], off offset:704
	s_and_b64 vcc, exec, s[6:7]
	s_cbranch_vccz .LBB0_680
	s_barrier
.LBB0_680:
	v_mov_b32_e32 v149, v126
	v_mov_b32_e32 v126, v123
	v_readlane_b32 s48, v254, 40
	s_lshl_b32 s46, s52, 7
	v_readlane_b32 s49, v254, 41
	s_ashr_i32 s47, s46, 31
	s_lshl_b64 s[46:47], s[46:47], 1
	s_waitcnt vmcnt(7)
	v_fmamk_f32 v80, v242, 0x3a800000, v194
	v_cmp_gt_f32_e32 vcc, s19, v80
	v_mul_f32_e32 v143, 0x4b800000, v80
	s_nop 0
	v_cndmask_b32_e32 v80, v80, v143, vcc
	v_rsq_f32_e32 v80, v80
	s_nop 0
	v_mul_f32_e32 v143, 0x45800000, v80
	v_cndmask_b32_e32 v80, v80, v143, vcc
	v_pk_mul_f32 v[148:149], v[148:149], v[80:81] op_sel_hi:[1,0]
	s_nop 0
	v_mul_f32_e32 v122, 0xbfb8aa3b, v149
	v_exp_f32_e32 v122, v122
	s_nop 0
	v_add_f32_e32 v122, 1.0, v122
	v_rcp_f32_e32 v122, v122
	s_nop 0
	v_mul_f32_e32 v122, v149, v122
	v_mul_f32_e32 v143, v148, v122
	v_pk_mul_f32 v[122:123], v[126:127], v[80:81] op_sel_hi:[1,0]
	s_nop 0
	v_mul_f32_e32 v126, 0xbfb8aa3b, v123
	v_exp_f32_e32 v126, v126
	s_nop 0
	v_add_f32_e32 v126, 1.0, v126
	v_rcp_f32_e32 v126, v126
	s_nop 0
	v_mul_f32_e32 v123, v123, v126
	v_mul_f32_e32 v126, v122, v123
	v_mov_b32_e32 v122, v124
	v_mov_b32_e32 v123, v128
	v_pk_mul_f32 v[122:123], v[122:123], v[80:81] op_sel_hi:[1,0]
	v_mov_b32_e32 v128, v125
	v_mul_f32_e32 v124, 0xbfb8aa3b, v123
	v_exp_f32_e32 v124, v124
	s_nop 0
	v_add_f32_e32 v124, 1.0, v124
	v_rcp_f32_e32 v124, v124
	s_nop 0
	v_mul_f32_e32 v123, v123, v124
	v_mul_f32_e32 v124, v122, v123
	v_pk_mul_f32 v[122:123], v[128:129], v[80:81] op_sel_hi:[1,0]
	s_nop 0
	v_mul_f32_e32 v125, 0xbfb8aa3b, v123
	v_exp_f32_e32 v125, v125
	s_nop 0
	v_add_f32_e32 v125, 1.0, v125
	v_rcp_f32_e32 v125, v125
	s_nop 0
	v_mul_f32_e32 v123, v123, v125
	v_mul_f32_e32 v125, v122, v123
	v_mov_b32_e32 v122, v114
	v_mov_b32_e32 v123, v118
	v_pk_mul_f32 v[122:123], v[122:123], v[80:81] op_sel_hi:[1,0]
	v_mov_b32_e32 v118, v115
	v_mul_f32_e32 v114, 0xbfb8aa3b, v123
	v_exp_f32_e32 v114, v114
	s_nop 0
	v_add_f32_e32 v114, 1.0, v114
	v_rcp_f32_e32 v114, v114
	s_nop 0
	v_mul_f32_e32 v114, v123, v114
	v_mul_f32_e32 v122, v122, v114
	v_pk_mul_f32 v[114:115], v[118:119], v[80:81] op_sel_hi:[1,0]
	s_nop 0
	v_mul_f32_e32 v118, 0xbfb8aa3b, v115
	v_exp_f32_e32 v118, v118
	s_nop 0
	v_add_f32_e32 v118, 1.0, v118
	v_rcp_f32_e32 v118, v118
	s_nop 0
	v_mul_f32_e32 v115, v115, v118
	v_mul_f32_e32 v118, v114, v115
	v_mov_b32_e32 v114, v116
	v_mov_b32_e32 v115, v120
	v_pk_mul_f32 v[114:115], v[114:115], v[80:81] op_sel_hi:[1,0]
	v_mov_b32_e32 v120, v117
	v_mul_f32_e32 v116, 0xbfb8aa3b, v115
	v_exp_f32_e32 v116, v116
	s_nop 0
	v_add_f32_e32 v116, 1.0, v116
	v_rcp_f32_e32 v116, v116
	s_nop 0
	v_mul_f32_e32 v115, v115, v116
	v_mul_f32_e32 v119, v114, v115
	v_pk_mul_f32 v[114:115], v[120:121], v[80:81] op_sel_hi:[1,0]
	s_nop 0
	v_mul_f32_e32 v80, 0xbfb8aa3b, v115
	v_exp_f32_e32 v80, v80
	s_nop 0
	v_add_f32_e32 v80, 1.0, v80
	v_rcp_f32_e32 v80, v80
	s_nop 0
	v_mul_f32_e32 v80, v115, v80
	v_mul_f32_e32 v80, v114, v80
	v_cvt_pk_bf16_f32 v114, v143, v126
	v_cvt_pk_bf16_f32 v115, v124, v125
	v_cvt_pk_bf16_f32 v116, v122, v118
	v_cvt_pk_bf16_f32 v117, v119, v80
	v_mov_b64_e32 v[118:119], s[48:49]
	v_mad_i64_i32 v[120:121], s[48:49], v142, s28, v[118:119]
	v_lshl_add_u64 v[120:121], v[120:121], 0, s[46:47]
	v_and_b32_e32 v80, 0xc0, v150
	v_lshl_add_u64 v[122:123], v[120:121], 0, v[80:81]
	v_and_b32_e32 v120, 48, v150
	v_mov_b32_e32 v121, v81
	v_lshl_add_u64 v[122:123], v[122:123], 0, v[120:121]
	global_store_dwordx4 v[122:123], v[114:117], off nt
	s_nop 0
	s_nop 0
	v_or_b32_e32 v115, 16, v142
	v_mov_b32_e32 v117, v110
	v_mov_b32_e32 v110, v107
	s_waitcnt vmcnt(7)
	v_fmamk_f32 v114, v243, 0x3a800000, v194
	v_cmp_gt_f32_e32 vcc, s19, v114
	v_mul_f32_e32 v116, 0x4b800000, v114
	s_nop 0
	v_cndmask_b32_e32 v114, v114, v116, vcc
	v_rsq_f32_e32 v114, v114
	s_nop 0
	v_mul_f32_e32 v116, 0x45800000, v114
	v_cndmask_b32_e32 v114, v114, v116, vcc
	v_mov_b32_e32 v116, v106
	v_pk_mul_f32 v[116:117], v[116:117], v[114:115] op_sel_hi:[1,0]
	s_nop 0
	v_mul_f32_e32 v106, 0xbfb8aa3b, v117
	v_exp_f32_e32 v106, v106
	s_nop 0
	v_add_f32_e32 v106, 1.0, v106
	v_rcp_f32_e32 v106, v106
	s_nop 0
	v_mul_f32_e32 v106, v117, v106
	v_mul_f32_e32 v116, v116, v106
	v_pk_mul_f32 v[106:107], v[110:111], v[114:115] op_sel_hi:[1,0]
	s_nop 0
	v_mul_f32_e32 v110, 0xbfb8aa3b, v107
	v_exp_f32_e32 v110, v110
	s_nop 0
	v_add_f32_e32 v110, 1.0, v110
	v_rcp_f32_e32 v110, v110
	s_nop 0
	v_mul_f32_e32 v107, v107, v110
	v_mul_f32_e32 v110, v106, v107
	v_mov_b32_e32 v106, v108
	v_mov_b32_e32 v107, v112
	v_pk_mul_f32 v[106:107], v[106:107], v[114:115] op_sel_hi:[1,0]
	v_mov_b32_e32 v112, v109
	v_mul_f32_e32 v108, 0xbfb8aa3b, v107
	v_exp_f32_e32 v108, v108
	s_nop 0
	v_add_f32_e32 v108, 1.0, v108
	v_rcp_f32_e32 v108, v108
	s_nop 0
	v_mul_f32_e32 v107, v107, v108
	v_mul_f32_e32 v108, v106, v107
	v_pk_mul_f32 v[106:107], v[112:113], v[114:115] op_sel_hi:[1,0]
	s_nop 0
	v_mul_f32_e32 v109, 0xbfb8aa3b, v107
	v_exp_f32_e32 v109, v109
	s_nop 0
	v_add_f32_e32 v109, 1.0, v109
	v_rcp_f32_e32 v109, v109
	s_nop 0
	v_mul_f32_e32 v107, v107, v109
	v_mul_f32_e32 v109, v106, v107
	v_mov_b32_e32 v106, v98
	v_mov_b32_e32 v107, v102
	v_pk_mul_f32 v[106:107], v[106:107], v[114:115] op_sel_hi:[1,0]
	v_mov_b32_e32 v102, v99
	v_mul_f32_e32 v98, 0xbfb8aa3b, v107
	v_exp_f32_e32 v98, v98
	s_nop 0
	v_add_f32_e32 v98, 1.0, v98
	v_rcp_f32_e32 v98, v98
	s_nop 0
	v_mul_f32_e32 v98, v107, v98
	v_mul_f32_e32 v106, v106, v98
	v_pk_mul_f32 v[98:99], v[102:103], v[114:115] op_sel_hi:[1,0]
	s_nop 0
	v_mul_f32_e32 v102, 0xbfb8aa3b, v99
	v_exp_f32_e32 v102, v102
	s_nop 0
	v_add_f32_e32 v102, 1.0, v102
	v_rcp_f32_e32 v102, v102
	s_nop 0
	v_mul_f32_e32 v99, v99, v102
	v_mul_f32_e32 v102, v98, v99
	v_mov_b32_e32 v98, v100
	v_mov_b32_e32 v99, v104
	v_pk_mul_f32 v[98:99], v[98:99], v[114:115] op_sel_hi:[1,0]
	v_mov_b32_e32 v104, v101
	v_mul_f32_e32 v100, 0xbfb8aa3b, v99
	v_exp_f32_e32 v100, v100
	s_nop 0
	v_add_f32_e32 v100, 1.0, v100
	v_rcp_f32_e32 v100, v100
	s_nop 0
	v_mul_f32_e32 v99, v99, v100
	v_mul_f32_e32 v103, v98, v99
	v_pk_mul_f32 v[98:99], v[104:105], v[114:115] op_sel_hi:[1,0]
	s_nop 0
	v_mul_f32_e32 v100, 0xbfb8aa3b, v99
	v_exp_f32_e32 v100, v100
	s_nop 0
	v_add_f32_e32 v100, 1.0, v100
	v_rcp_f32_e32 v100, v100
	s_nop 0
	v_mul_f32_e32 v99, v99, v100
	v_mul_f32_e32 v101, v98, v99
	v_cvt_pk_bf16_f32 v98, v116, v110
	v_cvt_pk_bf16_f32 v99, v108, v109
	v_cvt_pk_bf16_f32 v100, v106, v102
	v_cvt_pk_bf16_f32 v101, v103, v101
	v_mad_i64_i32 v[102:103], s[48:49], v115, s28, v[118:119]
	v_lshl_add_u64 v[102:103], v[102:103], 0, s[46:47]
	v_lshl_add_u64 v[102:103], v[102:103], 0, v[80:81]
	v_lshl_add_u64 v[102:103], v[102:103], 0, v[120:121]
	global_store_dwordx4 v[102:103], v[98:101], off nt
	s_nop 0
	s_nop 0
	v_or_b32_e32 v99, 32, v142
	v_mov_b32_e32 v101, v94
	v_mov_b32_e32 v94, v91
	s_waitcnt vmcnt(7)
	v_fmamk_f32 v98, v244, 0x3a800000, v194
	v_cmp_gt_f32_e32 vcc, s19, v98
	v_mul_f32_e32 v100, 0x4b800000, v98
	s_nop 0
	v_cndmask_b32_e32 v98, v98, v100, vcc
	v_rsq_f32_e32 v98, v98
	s_nop 0
	v_mul_f32_e32 v100, 0x45800000, v98
	v_cndmask_b32_e32 v98, v98, v100, vcc
	v_mov_b32_e32 v100, v90
	v_pk_mul_f32 v[100:101], v[100:101], v[98:99] op_sel_hi:[1,0]
	s_nop 0
	v_mul_f32_e32 v90, 0xbfb8aa3b, v101
	v_exp_f32_e32 v90, v90
	s_nop 0
	v_add_f32_e32 v90, 1.0, v90
	v_rcp_f32_e32 v90, v90
	s_nop 0
	v_mul_f32_e32 v90, v101, v90
	v_mul_f32_e32 v100, v100, v90
	v_pk_mul_f32 v[90:91], v[94:95], v[98:99] op_sel_hi:[1,0]
	s_nop 0
	v_mul_f32_e32 v94, 0xbfb8aa3b, v91
	v_exp_f32_e32 v94, v94
	s_nop 0
	v_add_f32_e32 v94, 1.0, v94
	v_rcp_f32_e32 v94, v94
	s_nop 0
	v_mul_f32_e32 v91, v91, v94
	v_mul_f32_e32 v94, v90, v91
	v_mov_b32_e32 v90, v92
	v_mov_b32_e32 v91, v96
	v_pk_mul_f32 v[90:91], v[90:91], v[98:99] op_sel_hi:[1,0]
	v_mov_b32_e32 v96, v93
	v_mul_f32_e32 v92, 0xbfb8aa3b, v91
	v_exp_f32_e32 v92, v92
	s_nop 0
	v_add_f32_e32 v92, 1.0, v92
	v_rcp_f32_e32 v92, v92
	s_nop 0
	v_mul_f32_e32 v91, v91, v92
	v_mul_f32_e32 v92, v90, v91
	v_pk_mul_f32 v[90:91], v[96:97], v[98:99] op_sel_hi:[1,0]
	s_nop 0
	v_mul_f32_e32 v93, 0xbfb8aa3b, v91
	v_exp_f32_e32 v93, v93
	s_nop 0
	v_add_f32_e32 v93, 1.0, v93
	v_rcp_f32_e32 v93, v93
	s_nop 0
	v_mul_f32_e32 v91, v91, v93
	v_mul_f32_e32 v93, v90, v91
	v_mov_b32_e32 v90, v82
	v_mov_b32_e32 v91, v86
	v_pk_mul_f32 v[90:91], v[90:91], v[98:99] op_sel_hi:[1,0]
	v_mov_b32_e32 v86, v83
	v_mul_f32_e32 v82, 0xbfb8aa3b, v91
	v_exp_f32_e32 v82, v82
	s_nop 0
	v_add_f32_e32 v82, 1.0, v82
	v_rcp_f32_e32 v82, v82
	s_nop 0
	v_mul_f32_e32 v82, v91, v82
	v_mul_f32_e32 v90, v90, v82
	v_pk_mul_f32 v[82:83], v[86:87], v[98:99] op_sel_hi:[1,0]
	s_nop 0
	v_mul_f32_e32 v86, 0xbfb8aa3b, v83
	v_exp_f32_e32 v86, v86
	s_nop 0
	v_add_f32_e32 v86, 1.0, v86
	v_rcp_f32_e32 v86, v86
	s_nop 0
	v_mul_f32_e32 v83, v83, v86
	v_mul_f32_e32 v86, v82, v83
	v_mov_b32_e32 v82, v84
	v_mov_b32_e32 v83, v88
	v_pk_mul_f32 v[82:83], v[82:83], v[98:99] op_sel_hi:[1,0]
	v_mov_b32_e32 v88, v85
	v_mul_f32_e32 v84, 0xbfb8aa3b, v83
	v_exp_f32_e32 v84, v84
	s_nop 0
	v_add_f32_e32 v84, 1.0, v84
	v_rcp_f32_e32 v84, v84
	s_nop 0
	v_mul_f32_e32 v83, v83, v84
	v_mul_f32_e32 v87, v82, v83
	v_pk_mul_f32 v[82:83], v[88:89], v[98:99] op_sel_hi:[1,0]
	s_nop 0
	v_mul_f32_e32 v84, 0xbfb8aa3b, v83
	v_exp_f32_e32 v84, v84
	s_nop 0
	v_add_f32_e32 v84, 1.0, v84
	v_rcp_f32_e32 v84, v84
	s_nop 0
	v_mul_f32_e32 v83, v83, v84
	v_mul_f32_e32 v85, v82, v83
	v_cvt_pk_bf16_f32 v82, v100, v94
	v_cvt_pk_bf16_f32 v83, v92, v93
	v_cvt_pk_bf16_f32 v84, v90, v86
	v_cvt_pk_bf16_f32 v85, v87, v85
	v_mad_i64_i32 v[86:87], s[48:49], v99, s28, v[118:119]
	v_lshl_add_u64 v[86:87], v[86:87], 0, s[46:47]
	v_lshl_add_u64 v[86:87], v[86:87], 0, v[80:81]
	v_lshl_add_u64 v[86:87], v[86:87], 0, v[120:121]
	global_store_dwordx4 v[86:87], v[82:85], off nt
	s_nop 0
	s_nop 0
	v_or_b32_e32 v83, 48, v142
	v_mov_b32_e32 v85, v76
	v_mov_b32_e32 v76, v73
	s_waitcnt vmcnt(7)
	v_fmamk_f32 v82, v245, 0x3a800000, v194
	v_cmp_gt_f32_e32 vcc, s19, v82
	v_mul_f32_e32 v84, 0x4b800000, v82
	s_nop 0
	v_cndmask_b32_e32 v82, v82, v84, vcc
	v_rsq_f32_e32 v82, v82
	s_nop 0
	v_mul_f32_e32 v84, 0x45800000, v82
	v_cndmask_b32_e32 v82, v82, v84, vcc
	v_mov_b32_e32 v84, v72
	v_pk_mul_f32 v[84:85], v[84:85], v[82:83] op_sel_hi:[1,0]
	s_nop 0
	v_mul_f32_e32 v72, 0xbfb8aa3b, v85
	v_exp_f32_e32 v72, v72
	s_nop 0
	v_add_f32_e32 v72, 1.0, v72
	v_rcp_f32_e32 v72, v72
	s_nop 0
	v_mul_f32_e32 v72, v85, v72
	v_mul_f32_e32 v84, v84, v72
	v_pk_mul_f32 v[72:73], v[76:77], v[82:83] op_sel_hi:[1,0]
	s_nop 0
	v_mul_f32_e32 v76, 0xbfb8aa3b, v73
	v_exp_f32_e32 v76, v76
	s_nop 0
	v_add_f32_e32 v76, 1.0, v76
	v_rcp_f32_e32 v76, v76
	s_nop 0
	v_mul_f32_e32 v73, v73, v76
	v_mul_f32_e32 v76, v72, v73
	v_mov_b32_e32 v72, v74
	v_mov_b32_e32 v73, v78
	v_pk_mul_f32 v[72:73], v[72:73], v[82:83] op_sel_hi:[1,0]
	v_mov_b32_e32 v78, v75
	v_mul_f32_e32 v74, 0xbfb8aa3b, v73
	v_exp_f32_e32 v74, v74
	s_nop 0
	v_add_f32_e32 v74, 1.0, v74
	v_rcp_f32_e32 v74, v74
	s_nop 0
	v_mul_f32_e32 v73, v73, v74
	v_mul_f32_e32 v74, v72, v73
	v_pk_mul_f32 v[72:73], v[78:79], v[82:83] op_sel_hi:[1,0]
	s_nop 0
	v_mul_f32_e32 v75, 0xbfb8aa3b, v73
	v_exp_f32_e32 v75, v75
	s_nop 0
	v_add_f32_e32 v75, 1.0, v75
	v_rcp_f32_e32 v75, v75
	s_nop 0
	v_mul_f32_e32 v73, v73, v75
	v_mul_f32_e32 v75, v72, v73
	v_mov_b32_e32 v72, v64
	v_mov_b32_e32 v73, v68
	v_pk_mul_f32 v[72:73], v[72:73], v[82:83] op_sel_hi:[1,0]
	v_mov_b32_e32 v68, v65
	v_mul_f32_e32 v64, 0xbfb8aa3b, v73
	v_exp_f32_e32 v64, v64
	s_nop 0
	v_add_f32_e32 v64, 1.0, v64
	v_rcp_f32_e32 v64, v64
	s_nop 0
	v_mul_f32_e32 v64, v73, v64
	v_mul_f32_e32 v72, v72, v64
	v_pk_mul_f32 v[64:65], v[68:69], v[82:83] op_sel_hi:[1,0]
	s_nop 0
	v_mul_f32_e32 v68, 0xbfb8aa3b, v65
	v_exp_f32_e32 v68, v68
	s_nop 0
	v_add_f32_e32 v68, 1.0, v68
	v_rcp_f32_e32 v68, v68
	s_nop 0
	v_mul_f32_e32 v65, v65, v68
	v_mul_f32_e32 v68, v64, v65
	v_mov_b32_e32 v64, v66
	v_mov_b32_e32 v65, v70
	v_pk_mul_f32 v[64:65], v[64:65], v[82:83] op_sel_hi:[1,0]
	v_mov_b32_e32 v70, v67
	v_mul_f32_e32 v66, 0xbfb8aa3b, v65
	v_exp_f32_e32 v66, v66
	s_nop 0
	v_add_f32_e32 v66, 1.0, v66
	v_rcp_f32_e32 v66, v66
	s_nop 0
	v_mul_f32_e32 v65, v65, v66
	v_mul_f32_e32 v69, v64, v65
	v_pk_mul_f32 v[64:65], v[70:71], v[82:83] op_sel_hi:[1,0]
	s_nop 0
	v_mul_f32_e32 v66, 0xbfb8aa3b, v65
	v_exp_f32_e32 v66, v66
	s_nop 0
	v_add_f32_e32 v66, 1.0, v66
	v_rcp_f32_e32 v66, v66
	s_nop 0
	v_mul_f32_e32 v65, v65, v66
	v_mul_f32_e32 v67, v64, v65
	v_cvt_pk_bf16_f32 v64, v84, v76
	v_cvt_pk_bf16_f32 v65, v74, v75
	v_cvt_pk_bf16_f32 v66, v72, v68
	v_cvt_pk_bf16_f32 v67, v69, v67
	v_mad_i64_i32 v[68:69], s[48:49], v83, s28, v[118:119]
	v_lshl_add_u64 v[68:69], v[68:69], 0, s[46:47]
	v_lshl_add_u64 v[68:69], v[68:69], 0, v[80:81]
	v_lshl_add_u64 v[68:69], v[68:69], 0, v[120:121]
	global_store_dwordx4 v[68:69], v[64:67], off nt
	s_nop 0
	s_nop 0
	v_add_u32_e32 v65, 0x80, v142
	v_mov_b32_e32 v67, v60
	v_mov_b32_e32 v60, v57
	s_waitcnt vmcnt(7)
	v_fmamk_f32 v64, v246, 0x3a800000, v194
	v_cmp_gt_f32_e32 vcc, s19, v64
	v_mul_f32_e32 v66, 0x4b800000, v64
	s_nop 0
	v_cndmask_b32_e32 v64, v64, v66, vcc
	v_rsq_f32_e32 v64, v64
	s_nop 0
	v_mul_f32_e32 v66, 0x45800000, v64
	v_cndmask_b32_e32 v64, v64, v66, vcc
	v_mov_b32_e32 v66, v56
	v_pk_mul_f32 v[66:67], v[66:67], v[64:65] op_sel_hi:[1,0]
	s_nop 0
	v_mul_f32_e32 v56, 0xbfb8aa3b, v67
	v_exp_f32_e32 v56, v56
	s_nop 0
	v_add_f32_e32 v56, 1.0, v56
	v_rcp_f32_e32 v56, v56
	s_nop 0
	v_mul_f32_e32 v56, v67, v56
	v_mul_f32_e32 v66, v66, v56
	v_pk_mul_f32 v[56:57], v[60:61], v[64:65] op_sel_hi:[1,0]
	s_nop 0
	v_mul_f32_e32 v60, 0xbfb8aa3b, v57
	v_exp_f32_e32 v60, v60
	s_nop 0
	v_add_f32_e32 v60, 1.0, v60
	v_rcp_f32_e32 v60, v60
	s_nop 0
	v_mul_f32_e32 v57, v57, v60
	v_mul_f32_e32 v60, v56, v57
	v_mov_b32_e32 v56, v58
	v_mov_b32_e32 v57, v62
	v_pk_mul_f32 v[56:57], v[56:57], v[64:65] op_sel_hi:[1,0]
	v_mov_b32_e32 v62, v59
	v_mul_f32_e32 v58, 0xbfb8aa3b, v57
	v_exp_f32_e32 v58, v58
	s_nop 0
	v_add_f32_e32 v58, 1.0, v58
	v_rcp_f32_e32 v58, v58
	s_nop 0
	v_mul_f32_e32 v57, v57, v58
	v_mul_f32_e32 v58, v56, v57
	v_pk_mul_f32 v[56:57], v[62:63], v[64:65] op_sel_hi:[1,0]
	s_nop 0
	v_mul_f32_e32 v59, 0xbfb8aa3b, v57
	v_exp_f32_e32 v59, v59
	s_nop 0
	v_add_f32_e32 v59, 1.0, v59
	v_rcp_f32_e32 v59, v59
	s_nop 0
	v_mul_f32_e32 v57, v57, v59
	v_mul_f32_e32 v59, v56, v57
	v_mov_b32_e32 v56, v48
	v_mov_b32_e32 v57, v52
	v_pk_mul_f32 v[56:57], v[56:57], v[64:65] op_sel_hi:[1,0]
	v_mov_b32_e32 v52, v49
	v_mul_f32_e32 v48, 0xbfb8aa3b, v57
	v_exp_f32_e32 v48, v48
	s_nop 0
	v_add_f32_e32 v48, 1.0, v48
	v_rcp_f32_e32 v48, v48
	s_nop 0
	v_mul_f32_e32 v48, v57, v48
	v_mul_f32_e32 v56, v56, v48
	v_pk_mul_f32 v[48:49], v[52:53], v[64:65] op_sel_hi:[1,0]
	s_nop 0
	v_mul_f32_e32 v52, 0xbfb8aa3b, v49
	v_exp_f32_e32 v52, v52
	s_nop 0
	v_add_f32_e32 v52, 1.0, v52
	v_rcp_f32_e32 v52, v52
	s_nop 0
	v_mul_f32_e32 v49, v49, v52
	v_mul_f32_e32 v52, v48, v49
	v_mov_b32_e32 v48, v50
	v_mov_b32_e32 v49, v54
	v_pk_mul_f32 v[48:49], v[48:49], v[64:65] op_sel_hi:[1,0]
	v_mov_b32_e32 v54, v51
	v_mul_f32_e32 v50, 0xbfb8aa3b, v49
	v_exp_f32_e32 v50, v50
	s_nop 0
	v_add_f32_e32 v50, 1.0, v50
	v_rcp_f32_e32 v50, v50
	s_nop 0
	v_mul_f32_e32 v49, v49, v50
	v_mul_f32_e32 v53, v48, v49
	v_pk_mul_f32 v[48:49], v[54:55], v[64:65] op_sel_hi:[1,0]
	s_nop 0
	v_mul_f32_e32 v50, 0xbfb8aa3b, v49
	v_exp_f32_e32 v50, v50
	s_nop 0
	v_add_f32_e32 v50, 1.0, v50
	v_rcp_f32_e32 v50, v50
	s_nop 0
	v_mul_f32_e32 v49, v49, v50
	v_mul_f32_e32 v51, v48, v49
	v_cvt_pk_bf16_f32 v48, v66, v60
	v_cvt_pk_bf16_f32 v49, v58, v59
	v_cvt_pk_bf16_f32 v50, v56, v52
	v_cvt_pk_bf16_f32 v51, v53, v51
	v_mad_i64_i32 v[52:53], s[48:49], v65, s28, v[118:119]
	v_lshl_add_u64 v[52:53], v[52:53], 0, s[46:47]
	v_lshl_add_u64 v[52:53], v[52:53], 0, v[80:81]
	v_lshl_add_u64 v[52:53], v[52:53], 0, v[120:121]
	global_store_dwordx4 v[52:53], v[48:51], off nt
	s_nop 0
	s_nop 0
	v_add_u32_e32 v49, 0x90, v142
	v_mov_b32_e32 v51, v44
	v_mov_b32_e32 v44, v41
	s_waitcnt vmcnt(7)
	v_fmamk_f32 v48, v247, 0x3a800000, v194
	v_cmp_gt_f32_e32 vcc, s19, v48
	v_mul_f32_e32 v50, 0x4b800000, v48
	s_nop 0
	v_cndmask_b32_e32 v48, v48, v50, vcc
	v_rsq_f32_e32 v48, v48
	s_nop 0
	v_mul_f32_e32 v50, 0x45800000, v48
	v_cndmask_b32_e32 v48, v48, v50, vcc
	v_mov_b32_e32 v50, v40
	v_pk_mul_f32 v[50:51], v[50:51], v[48:49] op_sel_hi:[1,0]
	s_nop 0
	v_mul_f32_e32 v40, 0xbfb8aa3b, v51
	v_exp_f32_e32 v40, v40
	s_nop 0
	v_add_f32_e32 v40, 1.0, v40
	v_rcp_f32_e32 v40, v40
	s_nop 0
	v_mul_f32_e32 v40, v51, v40
	v_mul_f32_e32 v50, v50, v40
	v_pk_mul_f32 v[40:41], v[44:45], v[48:49] op_sel_hi:[1,0]
	s_nop 0
	v_mul_f32_e32 v44, 0xbfb8aa3b, v41
	v_exp_f32_e32 v44, v44
	s_nop 0
	v_add_f32_e32 v44, 1.0, v44
	v_rcp_f32_e32 v44, v44
	s_nop 0
	v_mul_f32_e32 v41, v41, v44
	v_mul_f32_e32 v44, v40, v41
	v_mov_b32_e32 v40, v42
	v_mov_b32_e32 v41, v46
	v_pk_mul_f32 v[40:41], v[40:41], v[48:49] op_sel_hi:[1,0]
	v_mov_b32_e32 v46, v43
	v_mul_f32_e32 v42, 0xbfb8aa3b, v41
	v_exp_f32_e32 v42, v42
	s_nop 0
	v_add_f32_e32 v42, 1.0, v42
	v_rcp_f32_e32 v42, v42
	s_nop 0
	v_mul_f32_e32 v41, v41, v42
	v_mul_f32_e32 v42, v40, v41
	v_pk_mul_f32 v[40:41], v[46:47], v[48:49] op_sel_hi:[1,0]
	s_nop 0
	v_mul_f32_e32 v43, 0xbfb8aa3b, v41
	v_exp_f32_e32 v43, v43
	s_nop 0
	v_add_f32_e32 v43, 1.0, v43
	v_rcp_f32_e32 v43, v43
	s_nop 0
	v_mul_f32_e32 v41, v41, v43
	v_mul_f32_e32 v43, v40, v41
	v_mov_b32_e32 v40, v32
	v_mov_b32_e32 v41, v36
	v_pk_mul_f32 v[40:41], v[40:41], v[48:49] op_sel_hi:[1,0]
	v_mov_b32_e32 v36, v33
	v_mul_f32_e32 v32, 0xbfb8aa3b, v41
	v_exp_f32_e32 v32, v32
	s_nop 0
	v_add_f32_e32 v32, 1.0, v32
	v_rcp_f32_e32 v32, v32
	s_nop 0
	v_mul_f32_e32 v32, v41, v32
	v_mul_f32_e32 v40, v40, v32
	v_pk_mul_f32 v[32:33], v[36:37], v[48:49] op_sel_hi:[1,0]
	s_nop 0
	v_mul_f32_e32 v36, 0xbfb8aa3b, v33
	v_exp_f32_e32 v36, v36
	s_nop 0
	v_add_f32_e32 v36, 1.0, v36
	v_rcp_f32_e32 v36, v36
	s_nop 0
	v_mul_f32_e32 v33, v33, v36
	v_mul_f32_e32 v36, v32, v33
	v_mov_b32_e32 v32, v34
	v_mov_b32_e32 v33, v38
	v_pk_mul_f32 v[32:33], v[32:33], v[48:49] op_sel_hi:[1,0]
	v_mov_b32_e32 v38, v35
	v_mul_f32_e32 v34, 0xbfb8aa3b, v33
	v_exp_f32_e32 v34, v34
	s_nop 0
	v_add_f32_e32 v34, 1.0, v34
	v_rcp_f32_e32 v34, v34
	s_nop 0
	v_mul_f32_e32 v33, v33, v34
	v_mul_f32_e32 v37, v32, v33
	v_pk_mul_f32 v[32:33], v[38:39], v[48:49] op_sel_hi:[1,0]
	s_nop 0
	v_mul_f32_e32 v34, 0xbfb8aa3b, v33
	v_exp_f32_e32 v34, v34
	s_nop 0
	v_add_f32_e32 v34, 1.0, v34
	v_rcp_f32_e32 v34, v34
	s_nop 0
	v_mul_f32_e32 v33, v33, v34
	v_mul_f32_e32 v35, v32, v33
	v_cvt_pk_bf16_f32 v32, v50, v44
	v_cvt_pk_bf16_f32 v33, v42, v43
	v_cvt_pk_bf16_f32 v34, v40, v36
	v_cvt_pk_bf16_f32 v35, v37, v35
	v_mad_i64_i32 v[36:37], s[48:49], v49, s28, v[118:119]
	v_lshl_add_u64 v[36:37], v[36:37], 0, s[46:47]
	v_lshl_add_u64 v[36:37], v[36:37], 0, v[80:81]
	v_lshl_add_u64 v[36:37], v[36:37], 0, v[120:121]
	global_store_dwordx4 v[36:37], v[32:35], off nt
	s_nop 0
	s_nop 0
	v_add_u32_e32 v33, 0xa0, v142
	v_mov_b32_e32 v35, v28
	v_mov_b32_e32 v28, v25
	s_waitcnt vmcnt(7)
	v_fmamk_f32 v32, v248, 0x3a800000, v194
	v_cmp_gt_f32_e32 vcc, s19, v32
	v_mul_f32_e32 v34, 0x4b800000, v32
	s_nop 0
	v_cndmask_b32_e32 v32, v32, v34, vcc
	v_rsq_f32_e32 v32, v32
	s_nop 0
	v_mul_f32_e32 v34, 0x45800000, v32
	v_cndmask_b32_e32 v32, v32, v34, vcc
	v_mov_b32_e32 v34, v24
	v_pk_mul_f32 v[34:35], v[34:35], v[32:33] op_sel_hi:[1,0]
	s_nop 0
	v_mul_f32_e32 v24, 0xbfb8aa3b, v35
	v_exp_f32_e32 v24, v24
	s_nop 0
	v_add_f32_e32 v24, 1.0, v24
	v_rcp_f32_e32 v24, v24
	s_nop 0
	v_mul_f32_e32 v24, v35, v24
	v_mul_f32_e32 v34, v34, v24
	v_pk_mul_f32 v[24:25], v[28:29], v[32:33] op_sel_hi:[1,0]
	s_nop 0
	v_mul_f32_e32 v28, 0xbfb8aa3b, v25
	v_exp_f32_e32 v28, v28
	s_nop 0
	v_add_f32_e32 v28, 1.0, v28
	v_rcp_f32_e32 v28, v28
	s_nop 0
	v_mul_f32_e32 v25, v25, v28
	v_mul_f32_e32 v28, v24, v25
	v_mov_b32_e32 v24, v26
	v_mov_b32_e32 v25, v30
	v_pk_mul_f32 v[24:25], v[24:25], v[32:33] op_sel_hi:[1,0]
	v_mov_b32_e32 v30, v27
	v_mul_f32_e32 v26, 0xbfb8aa3b, v25
	v_exp_f32_e32 v26, v26
	s_nop 0
	v_add_f32_e32 v26, 1.0, v26
	v_rcp_f32_e32 v26, v26
	s_nop 0
	v_mul_f32_e32 v25, v25, v26
	v_mul_f32_e32 v26, v24, v25
	v_pk_mul_f32 v[24:25], v[30:31], v[32:33] op_sel_hi:[1,0]
	s_nop 0
	v_mul_f32_e32 v27, 0xbfb8aa3b, v25
	v_exp_f32_e32 v27, v27
	s_nop 0
	v_add_f32_e32 v27, 1.0, v27
	v_rcp_f32_e32 v27, v27
	s_nop 0
	v_mul_f32_e32 v25, v25, v27
	v_mul_f32_e32 v27, v24, v25
	v_mov_b32_e32 v24, v16
	v_mov_b32_e32 v25, v20
	v_pk_mul_f32 v[24:25], v[24:25], v[32:33] op_sel_hi:[1,0]
	v_mov_b32_e32 v20, v17
	v_mul_f32_e32 v16, 0xbfb8aa3b, v25
	v_exp_f32_e32 v16, v16
	s_nop 0
	v_add_f32_e32 v16, 1.0, v16
	v_rcp_f32_e32 v16, v16
	s_nop 0
	v_mul_f32_e32 v16, v25, v16
	v_mul_f32_e32 v24, v24, v16
	v_pk_mul_f32 v[16:17], v[20:21], v[32:33] op_sel_hi:[1,0]
	s_nop 0
	v_mul_f32_e32 v20, 0xbfb8aa3b, v17
	v_exp_f32_e32 v20, v20
	s_nop 0
	v_add_f32_e32 v20, 1.0, v20
	v_rcp_f32_e32 v20, v20
	s_nop 0
	v_mul_f32_e32 v17, v17, v20
	v_mul_f32_e32 v20, v16, v17
	v_mov_b32_e32 v16, v18
	v_mov_b32_e32 v17, v22
	v_pk_mul_f32 v[16:17], v[16:17], v[32:33] op_sel_hi:[1,0]
	v_mov_b32_e32 v22, v19
	v_mul_f32_e32 v18, 0xbfb8aa3b, v17
	v_exp_f32_e32 v18, v18
	s_nop 0
	v_add_f32_e32 v18, 1.0, v18
	v_rcp_f32_e32 v18, v18
	s_nop 0
	v_mul_f32_e32 v17, v17, v18
	v_mul_f32_e32 v21, v16, v17
	v_pk_mul_f32 v[16:17], v[22:23], v[32:33] op_sel_hi:[1,0]
	s_nop 0
	v_mul_f32_e32 v18, 0xbfb8aa3b, v17
	v_exp_f32_e32 v18, v18
	s_nop 0
	v_add_f32_e32 v18, 1.0, v18
	v_rcp_f32_e32 v18, v18
	s_nop 0
	v_mul_f32_e32 v17, v17, v18
	v_mul_f32_e32 v19, v16, v17
	v_cvt_pk_bf16_f32 v16, v34, v28
	v_cvt_pk_bf16_f32 v17, v26, v27
	v_cvt_pk_bf16_f32 v18, v24, v20
	v_cvt_pk_bf16_f32 v19, v21, v19
	v_mad_i64_i32 v[20:21], s[48:49], v33, s28, v[118:119]
	v_lshl_add_u64 v[20:21], v[20:21], 0, s[46:47]
	v_lshl_add_u64 v[20:21], v[20:21], 0, v[80:81]
	v_lshl_add_u64 v[20:21], v[20:21], 0, v[120:121]
	global_store_dwordx4 v[20:21], v[16:19], off nt
	s_nop 0
	s_nop 0
	v_add_u32_e32 v17, 0xb0, v142
	v_mov_b32_e32 v19, v12
	v_mov_b32_e32 v12, v9
	s_waitcnt vmcnt(7)
	v_fmamk_f32 v16, v249, 0x3a800000, v194
	v_cmp_gt_f32_e32 vcc, s19, v16
	v_mul_f32_e32 v18, 0x4b800000, v16
	s_nop 0
	v_cndmask_b32_e32 v16, v16, v18, vcc
	v_rsq_f32_e32 v16, v16
	s_nop 0
	v_mul_f32_e32 v18, 0x45800000, v16
	v_cndmask_b32_e32 v16, v16, v18, vcc
	v_mov_b32_e32 v18, v8
	v_pk_mul_f32 v[18:19], v[18:19], v[16:17] op_sel_hi:[1,0]
	s_andn2_b64 vcc, exec, s[40:41]
	v_mul_f32_e32 v8, 0xbfb8aa3b, v19
	v_exp_f32_e32 v8, v8
	s_nop 0
	v_add_f32_e32 v8, 1.0, v8
	v_rcp_f32_e32 v8, v8
	s_nop 0
	v_mul_f32_e32 v8, v19, v8
	v_mul_f32_e32 v18, v18, v8
	v_pk_mul_f32 v[8:9], v[12:13], v[16:17] op_sel_hi:[1,0]
	s_nop 0
	v_mul_f32_e32 v12, 0xbfb8aa3b, v9
	v_exp_f32_e32 v12, v12
	s_nop 0
	v_add_f32_e32 v12, 1.0, v12
	v_rcp_f32_e32 v12, v12
	s_nop 0
	v_mul_f32_e32 v9, v9, v12
	v_mul_f32_e32 v12, v8, v9
	v_mov_b32_e32 v8, v10
	v_mov_b32_e32 v9, v14
	v_pk_mul_f32 v[8:9], v[8:9], v[16:17] op_sel_hi:[1,0]
	v_mov_b32_e32 v14, v11
	v_mul_f32_e32 v10, 0xbfb8aa3b, v9
	v_exp_f32_e32 v10, v10
	s_nop 0
	v_add_f32_e32 v10, 1.0, v10
	v_rcp_f32_e32 v10, v10
	s_nop 0
	v_mul_f32_e32 v9, v9, v10
	v_mul_f32_e32 v10, v8, v9
	v_pk_mul_f32 v[8:9], v[14:15], v[16:17] op_sel_hi:[1,0]
	s_nop 0
	v_mul_f32_e32 v11, 0xbfb8aa3b, v9
	v_exp_f32_e32 v11, v11
	s_nop 0
	v_add_f32_e32 v11, 1.0, v11
	v_rcp_f32_e32 v11, v11
	s_nop 0
	v_mul_f32_e32 v9, v9, v11
	v_mul_f32_e32 v11, v8, v9
	v_mov_b32_e32 v8, v0
	v_mov_b32_e32 v9, v4
	v_pk_mul_f32 v[8:9], v[8:9], v[16:17] op_sel_hi:[1,0]
	v_mov_b32_e32 v4, v1
	v_mul_f32_e32 v0, 0xbfb8aa3b, v9
	v_exp_f32_e32 v0, v0
	s_nop 0
	v_add_f32_e32 v0, 1.0, v0
	v_rcp_f32_e32 v0, v0
	s_nop 0
	v_mul_f32_e32 v0, v9, v0
	v_mul_f32_e32 v8, v8, v0
	v_pk_mul_f32 v[0:1], v[4:5], v[16:17] op_sel_hi:[1,0]
	s_nop 0
	v_mul_f32_e32 v4, 0xbfb8aa3b, v1
	v_exp_f32_e32 v4, v4
	s_nop 0
	v_add_f32_e32 v4, 1.0, v4
	v_rcp_f32_e32 v4, v4
	s_nop 0
	v_mul_f32_e32 v1, v1, v4
	v_mul_f32_e32 v4, v0, v1
	v_mov_b32_e32 v0, v2
	v_mov_b32_e32 v1, v6
	v_pk_mul_f32 v[0:1], v[0:1], v[16:17] op_sel_hi:[1,0]
	v_mov_b32_e32 v6, v3
	v_mul_f32_e32 v2, 0xbfb8aa3b, v1
	v_exp_f32_e32 v2, v2
	s_nop 0
	v_add_f32_e32 v2, 1.0, v2
	v_rcp_f32_e32 v2, v2
	s_nop 0
	v_mul_f32_e32 v1, v1, v2
	v_mul_f32_e32 v5, v0, v1
	v_pk_mul_f32 v[0:1], v[6:7], v[16:17] op_sel_hi:[1,0]
	s_nop 0
	v_mul_f32_e32 v2, 0xbfb8aa3b, v1
	v_exp_f32_e32 v2, v2
	s_nop 0
	v_add_f32_e32 v2, 1.0, v2
	v_rcp_f32_e32 v2, v2
	s_nop 0
	v_mul_f32_e32 v1, v1, v2
	v_mul_f32_e32 v3, v0, v1
	v_cvt_pk_bf16_f32 v0, v18, v12
	v_cvt_pk_bf16_f32 v1, v10, v11
	v_cvt_pk_bf16_f32 v2, v8, v4
	v_cvt_pk_bf16_f32 v3, v5, v3
	v_mad_i64_i32 v[4:5], s[48:49], v17, s28, v[118:119]
	v_lshl_add_u64 v[4:5], v[4:5], 0, s[46:47]
	v_lshl_add_u64 v[4:5], v[4:5], 0, v[80:81]
	v_lshl_add_u64 v[4:5], v[4:5], 0, v[120:121]
	s_mov_b64 s[46:47], -1
	global_store_dwordx4 v[4:5], v[0:3], off nt
	s_cbranch_vccnz .LBB0_673
	s_andn2_b64 vcc, exec, s[0:1]
	s_cbranch_vccnz .LBB0_672
	s_barrier
	s_branch .LBB0_672
